# static s_setprio 1 for waves 4-7 through attention, conv and rwkv-prep (phase C); s_setprio 3 on the scan compute waves inside their step block
# speedup vs baseline: 1.0381x; 1.0159x over previous
.LBB0_308:
	s_cmp_lg_u64 s[40:41], 0
	s_cbranch_scc0 .Lattn_prio_skip
	s_setprio 1

.LBB0_370:
	s_setprio 0
	s_waitcnt vmcnt(0)
	s_barrier
	s_mov_b64 s[18:19], exec
	v_readlane_b32 s4, v253, 4
	v_readlane_b32 s5, v253, 5
	s_and_b64 s[4:5], s[18:19], s[4:5]
	s_mov_b64 exec, s[4:5]
	s_cbranch_execz .LBB0_422
	v_readlane_b32 s1, v252, 25
	s_waitcnt vmcnt(0) expcnt(0) lgkmcnt(0)
	s_nop 0
	v_mov_b32_e32 v0, s1
	ds_read_b32 v2, v0
	v_readlane_b32 s1, v252, 26
	s_waitcnt lgkmcnt(0)
	v_cmp_ne_u32_e32 vcc, 0, v2
	v_mov_b32_e32 v0, s1
	ds_read_b32 v0, v0
	s_cbranch_vccnz .LBB0_386
	s_mov_b32 s1, 1
	s_branch .LBB0_374

.LBB0_452:
	s_setprio 3
	s_and_b32 s22, s12, 1
	s_mul_i32 s78, s22, 0xb200
	v_lshl_add_u32 v147, v79, 4, s78
	v_lshl_add_u32 v148, v113, 2, s78
	v_mov_b32_e32 v149, s78
	v_lshrrev_b32_e32 v119, 2, v79
	ds_read_b128 v[32:35], v147 offset:768
	ds_read_b128 v[36:39], v147 offset:1024
	ds_read_b128 v[24:27], v147 offset:256
	ds_read_b64 v[60:61], v148 offset:1280
	ds_read_b128 v[28:31], v147 offset:512
	ds_read_b128 v[20:23], v147 offset:0
	ds_read_b64 v[64:65], v149 offset:1408
	s_waitcnt vmcnt(0)
	s_waitcnt lgkmcnt(0)
	ds_read_b128 v[52:55], v147 offset:2192
	ds_read_b128 v[56:59], v147 offset:2448
	ds_read_b128 v[44:47], v147 offset:1680
	ds_read_b64 v[62:63], v148 offset:2704
	ds_read_b128 v[48:51], v147 offset:1936
	ds_read_b128 v[40:43], v147 offset:1424
	ds_read_b64 v[66:67], v149 offset:2832
	v_mul_f32_e32 v120, v12, v32
	v_mul_f32_e32 v121, v16, v32
	v_mul_f32_e32 v122, v12, v36
	v_mul_f32_e32 v123, v16, v36
	v_fmac_f32_e32 v120, v13, v33
	v_fmac_f32_e32 v121, v17, v33
	v_fmac_f32_e32 v122, v13, v37
	v_fmac_f32_e32 v123, v17, v37
	v_fmac_f32_e32 v120, v14, v34
	v_fmac_f32_e32 v121, v18, v34
	v_fmac_f32_e32 v122, v14, v38
	v_fmac_f32_e32 v123, v18, v38
	v_fmac_f32_e32 v120, v15, v35
	v_fmac_f32_e32 v121, v19, v35
	v_fmac_f32_e32 v122, v15, v39
	v_fmac_f32_e32 v123, v19, v39
	v_cndmask_b32_e64 v124, v120, v121, s[42:43]
	v_cndmask_b32_e64 v126, v122, v123, s[42:43]
	v_cndmask_b32_e64 v125, v121, v120, s[42:43]
	v_cndmask_b32_e64 v127, v123, v122, s[42:43]
	v_add_f32_dpp v124, v124, v125 quad_perm:[1,0,3,2] row_mask:0xf bank_mask:0xf bound_ctrl:1
	v_add_f32_dpp v126, v126, v127 quad_perm:[1,0,3,2] row_mask:0xf bank_mask:0xf bound_ctrl:1
	v_cndmask_b32_e64 v128, v124, v126, s[44:45]
	v_cndmask_b32_e64 v129, v126, v124, s[44:45]
	v_pk_mul_f32 v[136:137], v[24:25], v[60:61] op_sel_hi:[1,0]
	v_add_f32_dpp v130, v128, v129 quad_perm:[2,3,0,1] row_mask:0xf bank_mask:0xf bound_ctrl:1
	v_pk_mul_f32 v[138:139], v[26:27], v[60:61] op_sel_hi:[1,0]
	v_pk_mul_f32 v[140:141], v[24:25], v[60:61] op_sel:[0,1]
	v_add_f32_dpp v130, v130, v130 row_ror:4 row_mask:0xf bank_mask:0xf bound_ctrl:1
	v_pk_mul_f32 v[142:143], v[26:27], v[60:61] op_sel:[0,1]
	v_cndmask_b32_e64 v145, v61, v60, s[42:43]
	v_add_f32_dpp v130, v130, v130 row_ror:8 row_mask:0xf bank_mask:0xf bound_ctrl:1
	s_nop 0
	v_cmp_eq_u32_e32 vcc, 0, v119
	v_mov_b32_dpp v132, v130 quad_perm:[0,0,0,0] row_mask:0xf bank_mask:0xf bound_ctrl:1
	v_mov_b32_dpp v134, v130 quad_perm:[1,1,1,1] row_mask:0xf bank_mask:0xf bound_ctrl:1
	v_pk_fma_f32 v[136:137], v[28:29], v[132:133], v[136:137] op_sel_hi:[1,0,1]
	v_pk_fma_f32 v[138:139], v[30:31], v[132:133], v[138:139] op_sel_hi:[1,0,1]
	v_pk_fma_f32 v[140:141], v[28:29], v[134:135], v[140:141] op_sel_hi:[1,0,1]
	v_pk_fma_f32 v[142:143], v[30:31], v[134:135], v[142:143] op_sel_hi:[1,0,1]
	v_cndmask_b32_e64 v144, v134, v132, s[42:43]
	v_pk_fma_f32 v[12:13], v[12:13], v[20:21], v[136:137]
	v_pk_fma_f32 v[14:15], v[14:15], v[22:23], v[138:139]
	v_fma_f32 v146, v145, v65, v130
	v_pk_fma_f32 v[16:17], v[16:17], v[20:21], v[140:141]
	v_pk_fma_f32 v[18:19], v[18:19], v[22:23], v[142:143]
	v_fmac_f32_e32 v146, v144, v64
	s_waitcnt lgkmcnt(0)
	ds_read_b128 v[32:35], v147 offset:3616
	ds_read_b128 v[36:39], v147 offset:3872
	ds_read_b128 v[24:27], v147 offset:3104
	ds_read_b64 v[60:61], v148 offset:4128
	ds_read_b128 v[28:31], v147 offset:3360
	ds_read_b128 v[20:23], v147 offset:2848
	ds_read_b64 v[64:65], v149 offset:4256
	v_mul_f32_e32 v120, v12, v52
	v_mul_f32_e32 v121, v16, v52
	v_mul_f32_e32 v122, v12, v56
	v_mul_f32_e32 v123, v16, v56
	v_fmac_f32_e32 v120, v13, v53
	v_fmac_f32_e32 v121, v17, v53
	v_fmac_f32_e32 v122, v13, v57
	v_fmac_f32_e32 v123, v17, v57
	v_fmac_f32_e32 v120, v14, v54
	v_fmac_f32_e32 v121, v18, v54
	v_fmac_f32_e32 v122, v14, v58
	v_fmac_f32_e32 v123, v18, v58
	v_fmac_f32_e32 v120, v15, v55
	v_fmac_f32_e32 v121, v19, v55
	v_fmac_f32_e32 v122, v15, v59
	v_fmac_f32_e32 v123, v19, v59
	v_cndmask_b32_e64 v124, v120, v121, s[42:43]
	v_cndmask_b32_e64 v126, v122, v123, s[42:43]
	v_cndmask_b32_e64 v125, v121, v120, s[42:43]
	v_cndmask_b32_e64 v127, v123, v122, s[42:43]
	v_add_f32_dpp v124, v124, v125 quad_perm:[1,0,3,2] row_mask:0xf bank_mask:0xf bound_ctrl:1
	v_add_f32_dpp v126, v126, v127 quad_perm:[1,0,3,2] row_mask:0xf bank_mask:0xf bound_ctrl:1
	v_cndmask_b32_e64 v128, v124, v126, s[44:45]
	v_cndmask_b32_e64 v129, v126, v124, s[44:45]
	v_pk_mul_f32 v[136:137], v[44:45], v[62:63] op_sel_hi:[1,0]
	v_add_f32_dpp v130, v128, v129 quad_perm:[2,3,0,1] row_mask:0xf bank_mask:0xf bound_ctrl:1
	v_pk_mul_f32 v[138:139], v[46:47], v[62:63] op_sel_hi:[1,0]
	v_pk_mul_f32 v[140:141], v[44:45], v[62:63] op_sel:[0,1]
	v_add_f32_dpp v130, v130, v130 row_ror:4 row_mask:0xf bank_mask:0xf bound_ctrl:1
	v_pk_mul_f32 v[142:143], v[46:47], v[62:63] op_sel:[0,1]
	v_cndmask_b32_e64 v145, v63, v62, s[42:43]
	v_add_f32_dpp v130, v130, v130 row_ror:8 row_mask:0xf bank_mask:0xf bound_ctrl:1
	v_cndmask_b32_e32 v0, v0, v146, vcc
	s_nop 0
	v_mov_b32_dpp v132, v130 quad_perm:[0,0,0,0] row_mask:0xf bank_mask:0xf bound_ctrl:1
	v_mov_b32_dpp v134, v130 quad_perm:[1,1,1,1] row_mask:0xf bank_mask:0xf bound_ctrl:1
	v_pk_fma_f32 v[136:137], v[48:49], v[132:133], v[136:137] op_sel_hi:[1,0,1]
	v_pk_fma_f32 v[138:139], v[50:51], v[132:133], v[138:139] op_sel_hi:[1,0,1]
	v_pk_fma_f32 v[140:141], v[48:49], v[134:135], v[140:141] op_sel_hi:[1,0,1]
	v_pk_fma_f32 v[142:143], v[50:51], v[134:135], v[142:143] op_sel_hi:[1,0,1]
	v_cndmask_b32_e64 v144, v134, v132, s[42:43]
	v_pk_fma_f32 v[12:13], v[12:13], v[40:41], v[136:137]
	v_pk_fma_f32 v[14:15], v[14:15], v[42:43], v[138:139]
	v_fma_f32 v150, v145, v67, v130
	v_pk_fma_f32 v[16:17], v[16:17], v[40:41], v[140:141]
	v_pk_fma_f32 v[18:19], v[18:19], v[42:43], v[142:143]
	v_fmac_f32_e32 v150, v144, v66
	s_waitcnt lgkmcnt(0)
	ds_read_b128 v[52:55], v147 offset:5040
	ds_read_b128 v[56:59], v147 offset:5296
	ds_read_b128 v[44:47], v147 offset:4528
	ds_read_b64 v[62:63], v148 offset:5552
	ds_read_b128 v[48:51], v147 offset:4784
	ds_read_b128 v[40:43], v147 offset:4272
	ds_read_b64 v[66:67], v149 offset:5680
	v_mul_f32_e32 v120, v12, v32
	v_mul_f32_e32 v121, v16, v32
	v_mul_f32_e32 v122, v12, v36
	v_mul_f32_e32 v123, v16, v36
	v_fmac_f32_e32 v120, v13, v33
	v_fmac_f32_e32 v121, v17, v33
	v_fmac_f32_e32 v122, v13, v37
	v_fmac_f32_e32 v123, v17, v37
	v_fmac_f32_e32 v120, v14, v34
	v_fmac_f32_e32 v121, v18, v34
	v_fmac_f32_e32 v122, v14, v38
	v_fmac_f32_e32 v123, v18, v38
	v_fmac_f32_e32 v120, v15, v35
	v_fmac_f32_e32 v121, v19, v35
	v_fmac_f32_e32 v122, v15, v39
	v_fmac_f32_e32 v123, v19, v39
	v_cndmask_b32_e64 v124, v120, v121, s[42:43]
	v_cndmask_b32_e64 v126, v122, v123, s[42:43]
	v_cndmask_b32_e64 v125, v121, v120, s[42:43]
	v_cndmask_b32_e64 v127, v123, v122, s[42:43]
	v_add_f32_dpp v124, v124, v125 quad_perm:[1,0,3,2] row_mask:0xf bank_mask:0xf bound_ctrl:1
	v_add_f32_dpp v126, v126, v127 quad_perm:[1,0,3,2] row_mask:0xf bank_mask:0xf bound_ctrl:1
	v_cndmask_b32_e64 v128, v124, v126, s[44:45]
	v_cndmask_b32_e64 v129, v126, v124, s[44:45]
	v_pk_mul_f32 v[136:137], v[24:25], v[60:61] op_sel_hi:[1,0]
	v_add_f32_dpp v130, v128, v129 quad_perm:[2,3,0,1] row_mask:0xf bank_mask:0xf bound_ctrl:1
	v_pk_mul_f32 v[138:139], v[26:27], v[60:61] op_sel_hi:[1,0]
	v_pk_mul_f32 v[140:141], v[24:25], v[60:61] op_sel:[0,1]
	v_add_f32_dpp v130, v130, v130 row_ror:4 row_mask:0xf bank_mask:0xf bound_ctrl:1
	v_pk_mul_f32 v[142:143], v[26:27], v[60:61] op_sel:[0,1]
	v_cndmask_b32_e64 v145, v61, v60, s[42:43]
	v_add_f32_dpp v130, v130, v130 row_ror:8 row_mask:0xf bank_mask:0xf bound_ctrl:1
	v_cndmask_b32_e32 v1, v1, v150, vcc
	s_nop 0
	v_mov_b32_dpp v132, v130 quad_perm:[0,0,0,0] row_mask:0xf bank_mask:0xf bound_ctrl:1
	v_mov_b32_dpp v134, v130 quad_perm:[1,1,1,1] row_mask:0xf bank_mask:0xf bound_ctrl:1
	v_pk_fma_f32 v[136:137], v[28:29], v[132:133], v[136:137] op_sel_hi:[1,0,1]
	v_pk_fma_f32 v[138:139], v[30:31], v[132:133], v[138:139] op_sel_hi:[1,0,1]
	v_pk_fma_f32 v[140:141], v[28:29], v[134:135], v[140:141] op_sel_hi:[1,0,1]
	v_pk_fma_f32 v[142:143], v[30:31], v[134:135], v[142:143] op_sel_hi:[1,0,1]
	v_cndmask_b32_e64 v144, v134, v132, s[42:43]
	v_pk_fma_f32 v[12:13], v[12:13], v[20:21], v[136:137]
	v_pk_fma_f32 v[14:15], v[14:15], v[22:23], v[138:139]
	v_fma_f32 v146, v145, v65, v130
	v_pk_fma_f32 v[16:17], v[16:17], v[20:21], v[140:141]
	v_pk_fma_f32 v[18:19], v[18:19], v[22:23], v[142:143]
	v_fmac_f32_e32 v146, v144, v64
	s_waitcnt lgkmcnt(0)
	ds_read_b128 v[32:35], v147 offset:6464
	ds_read_b128 v[36:39], v147 offset:6720
	ds_read_b128 v[24:27], v147 offset:5952
	ds_read_b64 v[60:61], v148 offset:6976
	ds_read_b128 v[28:31], v147 offset:6208
	ds_read_b128 v[20:23], v147 offset:5696
	ds_read_b64 v[64:65], v149 offset:7104
	v_mul_f32_e32 v120, v12, v52
	v_mul_f32_e32 v121, v16, v52
	v_mul_f32_e32 v122, v12, v56
	v_mul_f32_e32 v123, v16, v56
	v_fmac_f32_e32 v120, v13, v53
	v_fmac_f32_e32 v121, v17, v53
	v_fmac_f32_e32 v122, v13, v57
	v_fmac_f32_e32 v123, v17, v57
	v_fmac_f32_e32 v120, v14, v54
	v_fmac_f32_e32 v121, v18, v54
	v_fmac_f32_e32 v122, v14, v58
	v_fmac_f32_e32 v123, v18, v58
	v_fmac_f32_e32 v120, v15, v55
	v_fmac_f32_e32 v121, v19, v55
	v_fmac_f32_e32 v122, v15, v59
	v_fmac_f32_e32 v123, v19, v59
	v_cndmask_b32_e64 v124, v120, v121, s[42:43]
	v_cndmask_b32_e64 v126, v122, v123, s[42:43]
	v_cndmask_b32_e64 v125, v121, v120, s[42:43]
	v_cndmask_b32_e64 v127, v123, v122, s[42:43]
	v_add_f32_dpp v124, v124, v125 quad_perm:[1,0,3,2] row_mask:0xf bank_mask:0xf bound_ctrl:1
	v_add_f32_dpp v126, v126, v127 quad_perm:[1,0,3,2] row_mask:0xf bank_mask:0xf bound_ctrl:1
	v_cndmask_b32_e64 v128, v124, v126, s[44:45]
	v_cndmask_b32_e64 v129, v126, v124, s[44:45]
	v_pk_mul_f32 v[136:137], v[44:45], v[62:63] op_sel_hi:[1,0]
	v_add_f32_dpp v130, v128, v129 quad_perm:[2,3,0,1] row_mask:0xf bank_mask:0xf bound_ctrl:1
	v_pk_mul_f32 v[138:139], v[46:47], v[62:63] op_sel_hi:[1,0]
	v_pk_mul_f32 v[140:141], v[44:45], v[62:63] op_sel:[0,1]
	v_add_f32_dpp v130, v130, v130 row_ror:4 row_mask:0xf bank_mask:0xf bound_ctrl:1
	v_pk_mul_f32 v[142:143], v[46:47], v[62:63] op_sel:[0,1]
	v_cndmask_b32_e64 v145, v63, v62, s[42:43]
	v_add_f32_dpp v130, v130, v130 row_ror:8 row_mask:0xf bank_mask:0xf bound_ctrl:1
	v_cndmask_b32_e32 v2, v2, v146, vcc
	s_nop 0
	v_mov_b32_dpp v132, v130 quad_perm:[0,0,0,0] row_mask:0xf bank_mask:0xf bound_ctrl:1
	v_mov_b32_dpp v134, v130 quad_perm:[1,1,1,1] row_mask:0xf bank_mask:0xf bound_ctrl:1
	v_pk_fma_f32 v[136:137], v[48:49], v[132:133], v[136:137] op_sel_hi:[1,0,1]
	v_pk_fma_f32 v[138:139], v[50:51], v[132:133], v[138:139] op_sel_hi:[1,0,1]
	v_pk_fma_f32 v[140:141], v[48:49], v[134:135], v[140:141] op_sel_hi:[1,0,1]
	v_pk_fma_f32 v[142:143], v[50:51], v[134:135], v[142:143] op_sel_hi:[1,0,1]
	v_cndmask_b32_e64 v144, v134, v132, s[42:43]
	v_pk_fma_f32 v[12:13], v[12:13], v[40:41], v[136:137]
	v_pk_fma_f32 v[14:15], v[14:15], v[42:43], v[138:139]
	v_fma_f32 v150, v145, v67, v130
	v_pk_fma_f32 v[16:17], v[16:17], v[40:41], v[140:141]
	v_pk_fma_f32 v[18:19], v[18:19], v[42:43], v[142:143]
	v_fmac_f32_e32 v150, v144, v66
	s_waitcnt lgkmcnt(0)
	ds_read_b128 v[52:55], v147 offset:7888
	ds_read_b128 v[56:59], v147 offset:8144
	ds_read_b128 v[44:47], v147 offset:7376
	ds_read_b64 v[62:63], v148 offset:8400
	ds_read_b128 v[48:51], v147 offset:7632
	ds_read_b128 v[40:43], v147 offset:7120
	ds_read_b64 v[66:67], v149 offset:8528
	v_mul_f32_e32 v120, v12, v32
	v_mul_f32_e32 v121, v16, v32
	v_mul_f32_e32 v122, v12, v36
	v_mul_f32_e32 v123, v16, v36
	v_fmac_f32_e32 v120, v13, v33
	v_fmac_f32_e32 v121, v17, v33
	v_fmac_f32_e32 v122, v13, v37
	v_fmac_f32_e32 v123, v17, v37
	v_fmac_f32_e32 v120, v14, v34
	v_fmac_f32_e32 v121, v18, v34
	v_fmac_f32_e32 v122, v14, v38
	v_fmac_f32_e32 v123, v18, v38
	v_fmac_f32_e32 v120, v15, v35
	v_fmac_f32_e32 v121, v19, v35
	v_fmac_f32_e32 v122, v15, v39
	v_fmac_f32_e32 v123, v19, v39
	v_cndmask_b32_e64 v124, v120, v121, s[42:43]
	v_cndmask_b32_e64 v126, v122, v123, s[42:43]
	v_cndmask_b32_e64 v125, v121, v120, s[42:43]
	v_cndmask_b32_e64 v127, v123, v122, s[42:43]
	v_add_f32_dpp v124, v124, v125 quad_perm:[1,0,3,2] row_mask:0xf bank_mask:0xf bound_ctrl:1
	v_add_f32_dpp v126, v126, v127 quad_perm:[1,0,3,2] row_mask:0xf bank_mask:0xf bound_ctrl:1
	v_cndmask_b32_e64 v128, v124, v126, s[44:45]
	v_cndmask_b32_e64 v129, v126, v124, s[44:45]
	v_pk_mul_f32 v[136:137], v[24:25], v[60:61] op_sel_hi:[1,0]
	v_add_f32_dpp v130, v128, v129 quad_perm:[2,3,0,1] row_mask:0xf bank_mask:0xf bound_ctrl:1
	v_pk_mul_f32 v[138:139], v[26:27], v[60:61] op_sel_hi:[1,0]
	v_pk_mul_f32 v[140:141], v[24:25], v[60:61] op_sel:[0,1]
	v_add_f32_dpp v130, v130, v130 row_ror:4 row_mask:0xf bank_mask:0xf bound_ctrl:1
	v_pk_mul_f32 v[142:143], v[26:27], v[60:61] op_sel:[0,1]
	v_cndmask_b32_e64 v145, v61, v60, s[42:43]
	v_add_f32_dpp v130, v130, v130 row_ror:8 row_mask:0xf bank_mask:0xf bound_ctrl:1
	v_cndmask_b32_e32 v3, v3, v150, vcc
	v_cmp_eq_u32_e32 vcc, 1, v119
	v_mov_b32_dpp v132, v130 quad_perm:[0,0,0,0] row_mask:0xf bank_mask:0xf bound_ctrl:1
	v_mov_b32_dpp v134, v130 quad_perm:[1,1,1,1] row_mask:0xf bank_mask:0xf bound_ctrl:1
	v_pk_fma_f32 v[136:137], v[28:29], v[132:133], v[136:137] op_sel_hi:[1,0,1]
	v_pk_fma_f32 v[138:139], v[30:31], v[132:133], v[138:139] op_sel_hi:[1,0,1]
	v_pk_fma_f32 v[140:141], v[28:29], v[134:135], v[140:141] op_sel_hi:[1,0,1]
	v_pk_fma_f32 v[142:143], v[30:31], v[134:135], v[142:143] op_sel_hi:[1,0,1]
	v_cndmask_b32_e64 v144, v134, v132, s[42:43]
	v_pk_fma_f32 v[12:13], v[12:13], v[20:21], v[136:137]
	v_pk_fma_f32 v[14:15], v[14:15], v[22:23], v[138:139]
	v_fma_f32 v146, v145, v65, v130
	v_pk_fma_f32 v[16:17], v[16:17], v[20:21], v[140:141]
	v_pk_fma_f32 v[18:19], v[18:19], v[22:23], v[142:143]
	v_fmac_f32_e32 v146, v144, v64
	s_waitcnt lgkmcnt(0)
	ds_read_b128 v[32:35], v147 offset:9312
	ds_read_b128 v[36:39], v147 offset:9568
	ds_read_b128 v[24:27], v147 offset:8800
	ds_read_b64 v[60:61], v148 offset:9824
	ds_read_b128 v[28:31], v147 offset:9056
	ds_read_b128 v[20:23], v147 offset:8544
	ds_read_b64 v[64:65], v149 offset:9952
	v_mul_f32_e32 v120, v12, v52
	v_mul_f32_e32 v121, v16, v52
	v_mul_f32_e32 v122, v12, v56
	v_mul_f32_e32 v123, v16, v56
	v_fmac_f32_e32 v120, v13, v53
	v_fmac_f32_e32 v121, v17, v53
	v_fmac_f32_e32 v122, v13, v57
	v_fmac_f32_e32 v123, v17, v57
	v_fmac_f32_e32 v120, v14, v54
	v_fmac_f32_e32 v121, v18, v54
	v_fmac_f32_e32 v122, v14, v58
	v_fmac_f32_e32 v123, v18, v58
	v_fmac_f32_e32 v120, v15, v55
	v_fmac_f32_e32 v121, v19, v55
	v_fmac_f32_e32 v122, v15, v59
	v_fmac_f32_e32 v123, v19, v59
	v_cndmask_b32_e64 v124, v120, v121, s[42:43]
	v_cndmask_b32_e64 v126, v122, v123, s[42:43]
	v_cndmask_b32_e64 v125, v121, v120, s[42:43]
	v_cndmask_b32_e64 v127, v123, v122, s[42:43]
	v_add_f32_dpp v124, v124, v125 quad_perm:[1,0,3,2] row_mask:0xf bank_mask:0xf bound_ctrl:1
	v_add_f32_dpp v126, v126, v127 quad_perm:[1,0,3,2] row_mask:0xf bank_mask:0xf bound_ctrl:1
	v_cndmask_b32_e64 v128, v124, v126, s[44:45]
	v_cndmask_b32_e64 v129, v126, v124, s[44:45]
	v_pk_mul_f32 v[136:137], v[44:45], v[62:63] op_sel_hi:[1,0]
	v_add_f32_dpp v130, v128, v129 quad_perm:[2,3,0,1] row_mask:0xf bank_mask:0xf bound_ctrl:1
	v_pk_mul_f32 v[138:139], v[46:47], v[62:63] op_sel_hi:[1,0]
	v_pk_mul_f32 v[140:141], v[44:45], v[62:63] op_sel:[0,1]
	v_add_f32_dpp v130, v130, v130 row_ror:4 row_mask:0xf bank_mask:0xf bound_ctrl:1
	v_pk_mul_f32 v[142:143], v[46:47], v[62:63] op_sel:[0,1]
	v_cndmask_b32_e64 v145, v63, v62, s[42:43]
	v_add_f32_dpp v130, v130, v130 row_ror:8 row_mask:0xf bank_mask:0xf bound_ctrl:1
	v_cndmask_b32_e32 v0, v0, v146, vcc
	s_nop 0
	v_mov_b32_dpp v132, v130 quad_perm:[0,0,0,0] row_mask:0xf bank_mask:0xf bound_ctrl:1
	v_mov_b32_dpp v134, v130 quad_perm:[1,1,1,1] row_mask:0xf bank_mask:0xf bound_ctrl:1
	v_pk_fma_f32 v[136:137], v[48:49], v[132:133], v[136:137] op_sel_hi:[1,0,1]
	v_pk_fma_f32 v[138:139], v[50:51], v[132:133], v[138:139] op_sel_hi:[1,0,1]
	v_pk_fma_f32 v[140:141], v[48:49], v[134:135], v[140:141] op_sel_hi:[1,0,1]
	v_pk_fma_f32 v[142:143], v[50:51], v[134:135], v[142:143] op_sel_hi:[1,0,1]
	v_cndmask_b32_e64 v144, v134, v132, s[42:43]
	v_pk_fma_f32 v[12:13], v[12:13], v[40:41], v[136:137]
	v_pk_fma_f32 v[14:15], v[14:15], v[42:43], v[138:139]
	v_fma_f32 v150, v145, v67, v130
	v_pk_fma_f32 v[16:17], v[16:17], v[40:41], v[140:141]
	v_pk_fma_f32 v[18:19], v[18:19], v[42:43], v[142:143]
	v_fmac_f32_e32 v150, v144, v66
	s_waitcnt lgkmcnt(0)
	ds_read_b128 v[52:55], v147 offset:10736
	ds_read_b128 v[56:59], v147 offset:10992
	ds_read_b128 v[44:47], v147 offset:10224
	ds_read_b64 v[62:63], v148 offset:11248
	ds_read_b128 v[48:51], v147 offset:10480
	ds_read_b128 v[40:43], v147 offset:9968
	ds_read_b64 v[66:67], v149 offset:11376
	v_mul_f32_e32 v120, v12, v32
	v_mul_f32_e32 v121, v16, v32
	v_mul_f32_e32 v122, v12, v36
	v_mul_f32_e32 v123, v16, v36
	v_fmac_f32_e32 v120, v13, v33
	v_fmac_f32_e32 v121, v17, v33
	v_fmac_f32_e32 v122, v13, v37
	v_fmac_f32_e32 v123, v17, v37
	v_fmac_f32_e32 v120, v14, v34
	v_fmac_f32_e32 v121, v18, v34
	v_fmac_f32_e32 v122, v14, v38
	v_fmac_f32_e32 v123, v18, v38
	v_fmac_f32_e32 v120, v15, v35
	v_fmac_f32_e32 v121, v19, v35
	v_fmac_f32_e32 v122, v15, v39
	v_fmac_f32_e32 v123, v19, v39
	v_cndmask_b32_e64 v124, v120, v121, s[42:43]
	v_cndmask_b32_e64 v126, v122, v123, s[42:43]
	v_cndmask_b32_e64 v125, v121, v120, s[42:43]
	v_cndmask_b32_e64 v127, v123, v122, s[42:43]
	v_add_f32_dpp v124, v124, v125 quad_perm:[1,0,3,2] row_mask:0xf bank_mask:0xf bound_ctrl:1
	v_add_f32_dpp v126, v126, v127 quad_perm:[1,0,3,2] row_mask:0xf bank_mask:0xf bound_ctrl:1
	v_cndmask_b32_e64 v128, v124, v126, s[44:45]
	v_cndmask_b32_e64 v129, v126, v124, s[44:45]
	v_pk_mul_f32 v[136:137], v[24:25], v[60:61] op_sel_hi:[1,0]
	v_add_f32_dpp v130, v128, v129 quad_perm:[2,3,0,1] row_mask:0xf bank_mask:0xf bound_ctrl:1
	v_pk_mul_f32 v[138:139], v[26:27], v[60:61] op_sel_hi:[1,0]
	v_pk_mul_f32 v[140:141], v[24:25], v[60:61] op_sel:[0,1]
	v_add_f32_dpp v130, v130, v130 row_ror:4 row_mask:0xf bank_mask:0xf bound_ctrl:1
	v_pk_mul_f32 v[142:143], v[26:27], v[60:61] op_sel:[0,1]
	v_cndmask_b32_e64 v145, v61, v60, s[42:43]
	v_add_f32_dpp v130, v130, v130 row_ror:8 row_mask:0xf bank_mask:0xf bound_ctrl:1
	v_cndmask_b32_e32 v1, v1, v150, vcc
	s_nop 0
	v_mov_b32_dpp v132, v130 quad_perm:[0,0,0,0] row_mask:0xf bank_mask:0xf bound_ctrl:1
	v_mov_b32_dpp v134, v130 quad_perm:[1,1,1,1] row_mask:0xf bank_mask:0xf bound_ctrl:1
	v_pk_fma_f32 v[136:137], v[28:29], v[132:133], v[136:137] op_sel_hi:[1,0,1]
	v_pk_fma_f32 v[138:139], v[30:31], v[132:133], v[138:139] op_sel_hi:[1,0,1]
	v_pk_fma_f32 v[140:141], v[28:29], v[134:135], v[140:141] op_sel_hi:[1,0,1]
	v_pk_fma_f32 v[142:143], v[30:31], v[134:135], v[142:143] op_sel_hi:[1,0,1]
	v_cndmask_b32_e64 v144, v134, v132, s[42:43]
	v_pk_fma_f32 v[12:13], v[12:13], v[20:21], v[136:137]
	v_pk_fma_f32 v[14:15], v[14:15], v[22:23], v[138:139]
	v_fma_f32 v146, v145, v65, v130
	v_pk_fma_f32 v[16:17], v[16:17], v[20:21], v[140:141]
	v_pk_fma_f32 v[18:19], v[18:19], v[22:23], v[142:143]
	v_fmac_f32_e32 v146, v144, v64
	s_waitcnt lgkmcnt(0)
	ds_read_b128 v[32:35], v147 offset:12160
	ds_read_b128 v[36:39], v147 offset:12416
	ds_read_b128 v[24:27], v147 offset:11648
	ds_read_b64 v[60:61], v148 offset:12672
	ds_read_b128 v[28:31], v147 offset:11904
	ds_read_b128 v[20:23], v147 offset:11392
	ds_read_b64 v[64:65], v149 offset:12800
	v_mul_f32_e32 v120, v12, v52
	v_mul_f32_e32 v121, v16, v52
	v_mul_f32_e32 v122, v12, v56
	v_mul_f32_e32 v123, v16, v56
	v_fmac_f32_e32 v120, v13, v53
	v_fmac_f32_e32 v121, v17, v53
	v_fmac_f32_e32 v122, v13, v57
	v_fmac_f32_e32 v123, v17, v57
	v_fmac_f32_e32 v120, v14, v54
	v_fmac_f32_e32 v121, v18, v54
	v_fmac_f32_e32 v122, v14, v58
	v_fmac_f32_e32 v123, v18, v58
	v_fmac_f32_e32 v120, v15, v55
	v_fmac_f32_e32 v121, v19, v55
	v_fmac_f32_e32 v122, v15, v59
	v_fmac_f32_e32 v123, v19, v59
	v_cndmask_b32_e64 v124, v120, v121, s[42:43]
	v_cndmask_b32_e64 v126, v122, v123, s[42:43]
	v_cndmask_b32_e64 v125, v121, v120, s[42:43]
	v_cndmask_b32_e64 v127, v123, v122, s[42:43]
	v_add_f32_dpp v124, v124, v125 quad_perm:[1,0,3,2] row_mask:0xf bank_mask:0xf bound_ctrl:1
	v_add_f32_dpp v126, v126, v127 quad_perm:[1,0,3,2] row_mask:0xf bank_mask:0xf bound_ctrl:1
	v_cndmask_b32_e64 v128, v124, v126, s[44:45]
	v_cndmask_b32_e64 v129, v126, v124, s[44:45]
	v_pk_mul_f32 v[136:137], v[44:45], v[62:63] op_sel_hi:[1,0]
	v_add_f32_dpp v130, v128, v129 quad_perm:[2,3,0,1] row_mask:0xf bank_mask:0xf bound_ctrl:1
	v_pk_mul_f32 v[138:139], v[46:47], v[62:63] op_sel_hi:[1,0]
	v_pk_mul_f32 v[140:141], v[44:45], v[62:63] op_sel:[0,1]
	v_add_f32_dpp v130, v130, v130 row_ror:4 row_mask:0xf bank_mask:0xf bound_ctrl:1
	v_pk_mul_f32 v[142:143], v[46:47], v[62:63] op_sel:[0,1]
	v_cndmask_b32_e64 v145, v63, v62, s[42:43]
	v_add_f32_dpp v130, v130, v130 row_ror:8 row_mask:0xf bank_mask:0xf bound_ctrl:1
	v_cndmask_b32_e32 v2, v2, v146, vcc
	s_nop 0
	v_mov_b32_dpp v132, v130 quad_perm:[0,0,0,0] row_mask:0xf bank_mask:0xf bound_ctrl:1
	v_mov_b32_dpp v134, v130 quad_perm:[1,1,1,1] row_mask:0xf bank_mask:0xf bound_ctrl:1
	v_pk_fma_f32 v[136:137], v[48:49], v[132:133], v[136:137] op_sel_hi:[1,0,1]
	v_pk_fma_f32 v[138:139], v[50:51], v[132:133], v[138:139] op_sel_hi:[1,0,1]
	v_pk_fma_f32 v[140:141], v[48:49], v[134:135], v[140:141] op_sel_hi:[1,0,1]
	v_pk_fma_f32 v[142:143], v[50:51], v[134:135], v[142:143] op_sel_hi:[1,0,1]
	v_cndmask_b32_e64 v144, v134, v132, s[42:43]
	v_pk_fma_f32 v[12:13], v[12:13], v[40:41], v[136:137]
	v_pk_fma_f32 v[14:15], v[14:15], v[42:43], v[138:139]
	v_fma_f32 v150, v145, v67, v130
	v_pk_fma_f32 v[16:17], v[16:17], v[40:41], v[140:141]
	v_pk_fma_f32 v[18:19], v[18:19], v[42:43], v[142:143]
	v_fmac_f32_e32 v150, v144, v66
	s_waitcnt lgkmcnt(0)
	ds_read_b128 v[52:55], v147 offset:13584
	ds_read_b128 v[56:59], v147 offset:13840
	ds_read_b128 v[44:47], v147 offset:13072
	ds_read_b64 v[62:63], v148 offset:14096
	ds_read_b128 v[48:51], v147 offset:13328
	ds_read_b128 v[40:43], v147 offset:12816
	ds_read_b64 v[66:67], v149 offset:14224
	v_mul_f32_e32 v120, v12, v32
	v_mul_f32_e32 v121, v16, v32
	v_mul_f32_e32 v122, v12, v36
	v_mul_f32_e32 v123, v16, v36
	v_fmac_f32_e32 v120, v13, v33
	v_fmac_f32_e32 v121, v17, v33
	v_fmac_f32_e32 v122, v13, v37
	v_fmac_f32_e32 v123, v17, v37
	v_fmac_f32_e32 v120, v14, v34
	v_fmac_f32_e32 v121, v18, v34
	v_fmac_f32_e32 v122, v14, v38
	v_fmac_f32_e32 v123, v18, v38
	v_fmac_f32_e32 v120, v15, v35
	v_fmac_f32_e32 v121, v19, v35
	v_fmac_f32_e32 v122, v15, v39
	v_fmac_f32_e32 v123, v19, v39
	v_cndmask_b32_e64 v124, v120, v121, s[42:43]
	v_cndmask_b32_e64 v126, v122, v123, s[42:43]
	v_cndmask_b32_e64 v125, v121, v120, s[42:43]
	v_cndmask_b32_e64 v127, v123, v122, s[42:43]
	v_add_f32_dpp v124, v124, v125 quad_perm:[1,0,3,2] row_mask:0xf bank_mask:0xf bound_ctrl:1
	v_add_f32_dpp v126, v126, v127 quad_perm:[1,0,3,2] row_mask:0xf bank_mask:0xf bound_ctrl:1
	v_cndmask_b32_e64 v128, v124, v126, s[44:45]
	v_cndmask_b32_e64 v129, v126, v124, s[44:45]
	v_pk_mul_f32 v[136:137], v[24:25], v[60:61] op_sel_hi:[1,0]
	v_add_f32_dpp v130, v128, v129 quad_perm:[2,3,0,1] row_mask:0xf bank_mask:0xf bound_ctrl:1
	v_pk_mul_f32 v[138:139], v[26:27], v[60:61] op_sel_hi:[1,0]
	v_pk_mul_f32 v[140:141], v[24:25], v[60:61] op_sel:[0,1]
	v_add_f32_dpp v130, v130, v130 row_ror:4 row_mask:0xf bank_mask:0xf bound_ctrl:1
	v_pk_mul_f32 v[142:143], v[26:27], v[60:61] op_sel:[0,1]
	v_cndmask_b32_e64 v145, v61, v60, s[42:43]
	v_add_f32_dpp v130, v130, v130 row_ror:8 row_mask:0xf bank_mask:0xf bound_ctrl:1
	v_cndmask_b32_e32 v3, v3, v150, vcc
	v_cmp_eq_u32_e32 vcc, 2, v119
	v_mov_b32_dpp v132, v130 quad_perm:[0,0,0,0] row_mask:0xf bank_mask:0xf bound_ctrl:1
	v_mov_b32_dpp v134, v130 quad_perm:[1,1,1,1] row_mask:0xf bank_mask:0xf bound_ctrl:1
	v_pk_fma_f32 v[136:137], v[28:29], v[132:133], v[136:137] op_sel_hi:[1,0,1]
	v_pk_fma_f32 v[138:139], v[30:31], v[132:133], v[138:139] op_sel_hi:[1,0,1]
	v_pk_fma_f32 v[140:141], v[28:29], v[134:135], v[140:141] op_sel_hi:[1,0,1]
	v_pk_fma_f32 v[142:143], v[30:31], v[134:135], v[142:143] op_sel_hi:[1,0,1]
	v_cndmask_b32_e64 v144, v134, v132, s[42:43]
	v_pk_fma_f32 v[12:13], v[12:13], v[20:21], v[136:137]
	v_pk_fma_f32 v[14:15], v[14:15], v[22:23], v[138:139]
	v_fma_f32 v146, v145, v65, v130
	v_pk_fma_f32 v[16:17], v[16:17], v[20:21], v[140:141]
	v_pk_fma_f32 v[18:19], v[18:19], v[22:23], v[142:143]
	v_fmac_f32_e32 v146, v144, v64
	s_waitcnt lgkmcnt(0)
	ds_read_b128 v[32:35], v147 offset:15008
	ds_read_b128 v[36:39], v147 offset:15264
	ds_read_b128 v[24:27], v147 offset:14496
	ds_read_b64 v[60:61], v148 offset:15520
	ds_read_b128 v[28:31], v147 offset:14752
	ds_read_b128 v[20:23], v147 offset:14240
	ds_read_b64 v[64:65], v149 offset:15648
	v_mul_f32_e32 v120, v12, v52
	v_mul_f32_e32 v121, v16, v52
	v_mul_f32_e32 v122, v12, v56
	v_mul_f32_e32 v123, v16, v56
	v_fmac_f32_e32 v120, v13, v53
	v_fmac_f32_e32 v121, v17, v53
	v_fmac_f32_e32 v122, v13, v57
	v_fmac_f32_e32 v123, v17, v57
	v_fmac_f32_e32 v120, v14, v54
	v_fmac_f32_e32 v121, v18, v54
	v_fmac_f32_e32 v122, v14, v58
	v_fmac_f32_e32 v123, v18, v58
	v_fmac_f32_e32 v120, v15, v55
	v_fmac_f32_e32 v121, v19, v55
	v_fmac_f32_e32 v122, v15, v59
	v_fmac_f32_e32 v123, v19, v59
	v_cndmask_b32_e64 v124, v120, v121, s[42:43]
	v_cndmask_b32_e64 v126, v122, v123, s[42:43]
	v_cndmask_b32_e64 v125, v121, v120, s[42:43]
	v_cndmask_b32_e64 v127, v123, v122, s[42:43]
	v_add_f32_dpp v124, v124, v125 quad_perm:[1,0,3,2] row_mask:0xf bank_mask:0xf bound_ctrl:1
	v_add_f32_dpp v126, v126, v127 quad_perm:[1,0,3,2] row_mask:0xf bank_mask:0xf bound_ctrl:1
	v_cndmask_b32_e64 v128, v124, v126, s[44:45]
	v_cndmask_b32_e64 v129, v126, v124, s[44:45]
	v_pk_mul_f32 v[136:137], v[44:45], v[62:63] op_sel_hi:[1,0]
	v_add_f32_dpp v130, v128, v129 quad_perm:[2,3,0,1] row_mask:0xf bank_mask:0xf bound_ctrl:1
	v_pk_mul_f32 v[138:139], v[46:47], v[62:63] op_sel_hi:[1,0]
	v_pk_mul_f32 v[140:141], v[44:45], v[62:63] op_sel:[0,1]
	v_add_f32_dpp v130, v130, v130 row_ror:4 row_mask:0xf bank_mask:0xf bound_ctrl:1
	v_pk_mul_f32 v[142:143], v[46:47], v[62:63] op_sel:[0,1]
	v_cndmask_b32_e64 v145, v63, v62, s[42:43]
	v_add_f32_dpp v130, v130, v130 row_ror:8 row_mask:0xf bank_mask:0xf bound_ctrl:1
	v_cndmask_b32_e32 v0, v0, v146, vcc
	s_nop 0
	v_mov_b32_dpp v132, v130 quad_perm:[0,0,0,0] row_mask:0xf bank_mask:0xf bound_ctrl:1
	v_mov_b32_dpp v134, v130 quad_perm:[1,1,1,1] row_mask:0xf bank_mask:0xf bound_ctrl:1
	v_pk_fma_f32 v[136:137], v[48:49], v[132:133], v[136:137] op_sel_hi:[1,0,1]
	v_pk_fma_f32 v[138:139], v[50:51], v[132:133], v[138:139] op_sel_hi:[1,0,1]
	v_pk_fma_f32 v[140:141], v[48:49], v[134:135], v[140:141] op_sel_hi:[1,0,1]
	v_pk_fma_f32 v[142:143], v[50:51], v[134:135], v[142:143] op_sel_hi:[1,0,1]
	v_cndmask_b32_e64 v144, v134, v132, s[42:43]
	v_pk_fma_f32 v[12:13], v[12:13], v[40:41], v[136:137]
	v_pk_fma_f32 v[14:15], v[14:15], v[42:43], v[138:139]
	v_fma_f32 v150, v145, v67, v130
	v_pk_fma_f32 v[16:17], v[16:17], v[40:41], v[140:141]
	v_pk_fma_f32 v[18:19], v[18:19], v[42:43], v[142:143]
	v_fmac_f32_e32 v150, v144, v66
	s_waitcnt lgkmcnt(0)
	ds_read_b128 v[52:55], v147 offset:16432
	ds_read_b128 v[56:59], v147 offset:16688
	ds_read_b128 v[44:47], v147 offset:15920
	ds_read_b64 v[62:63], v148 offset:16944
	ds_read_b128 v[48:51], v147 offset:16176
	ds_read_b128 v[40:43], v147 offset:15664
	ds_read_b64 v[66:67], v149 offset:17072
	v_mul_f32_e32 v120, v12, v32
	v_mul_f32_e32 v121, v16, v32
	v_mul_f32_e32 v122, v12, v36
	v_mul_f32_e32 v123, v16, v36
	v_fmac_f32_e32 v120, v13, v33
	v_fmac_f32_e32 v121, v17, v33
	v_fmac_f32_e32 v122, v13, v37
	v_fmac_f32_e32 v123, v17, v37
	v_fmac_f32_e32 v120, v14, v34
	v_fmac_f32_e32 v121, v18, v34
	v_fmac_f32_e32 v122, v14, v38
	v_fmac_f32_e32 v123, v18, v38
	v_fmac_f32_e32 v120, v15, v35
	v_fmac_f32_e32 v121, v19, v35
	v_fmac_f32_e32 v122, v15, v39
	v_fmac_f32_e32 v123, v19, v39
	v_cndmask_b32_e64 v124, v120, v121, s[42:43]
	v_cndmask_b32_e64 v126, v122, v123, s[42:43]
	v_cndmask_b32_e64 v125, v121, v120, s[42:43]
	v_cndmask_b32_e64 v127, v123, v122, s[42:43]
	v_add_f32_dpp v124, v124, v125 quad_perm:[1,0,3,2] row_mask:0xf bank_mask:0xf bound_ctrl:1
	v_add_f32_dpp v126, v126, v127 quad_perm:[1,0,3,2] row_mask:0xf bank_mask:0xf bound_ctrl:1
	v_cndmask_b32_e64 v128, v124, v126, s[44:45]
	v_cndmask_b32_e64 v129, v126, v124, s[44:45]
	v_pk_mul_f32 v[136:137], v[24:25], v[60:61] op_sel_hi:[1,0]
	v_add_f32_dpp v130, v128, v129 quad_perm:[2,3,0,1] row_mask:0xf bank_mask:0xf bound_ctrl:1
	v_pk_mul_f32 v[138:139], v[26:27], v[60:61] op_sel_hi:[1,0]
	v_pk_mul_f32 v[140:141], v[24:25], v[60:61] op_sel:[0,1]
	v_add_f32_dpp v130, v130, v130 row_ror:4 row_mask:0xf bank_mask:0xf bound_ctrl:1
	v_pk_mul_f32 v[142:143], v[26:27], v[60:61] op_sel:[0,1]
	v_cndmask_b32_e64 v145, v61, v60, s[42:43]
	v_add_f32_dpp v130, v130, v130 row_ror:8 row_mask:0xf bank_mask:0xf bound_ctrl:1
	v_cndmask_b32_e32 v1, v1, v150, vcc
	s_nop 0
	v_mov_b32_dpp v132, v130 quad_perm:[0,0,0,0] row_mask:0xf bank_mask:0xf bound_ctrl:1
	v_mov_b32_dpp v134, v130 quad_perm:[1,1,1,1] row_mask:0xf bank_mask:0xf bound_ctrl:1
	v_pk_fma_f32 v[136:137], v[28:29], v[132:133], v[136:137] op_sel_hi:[1,0,1]
	v_pk_fma_f32 v[138:139], v[30:31], v[132:133], v[138:139] op_sel_hi:[1,0,1]
	v_pk_fma_f32 v[140:141], v[28:29], v[134:135], v[140:141] op_sel_hi:[1,0,1]
	v_pk_fma_f32 v[142:143], v[30:31], v[134:135], v[142:143] op_sel_hi:[1,0,1]
	v_cndmask_b32_e64 v144, v134, v132, s[42:43]
	v_pk_fma_f32 v[12:13], v[12:13], v[20:21], v[136:137]
	v_pk_fma_f32 v[14:15], v[14:15], v[22:23], v[138:139]
	v_fma_f32 v146, v145, v65, v130
	v_pk_fma_f32 v[16:17], v[16:17], v[20:21], v[140:141]
	v_pk_fma_f32 v[18:19], v[18:19], v[22:23], v[142:143]
	v_fmac_f32_e32 v146, v144, v64
	s_waitcnt lgkmcnt(0)
	ds_read_b128 v[32:35], v147 offset:17856
	ds_read_b128 v[36:39], v147 offset:18112
	ds_read_b128 v[24:27], v147 offset:17344
	ds_read_b64 v[60:61], v148 offset:18368
	ds_read_b128 v[28:31], v147 offset:17600
	ds_read_b128 v[20:23], v147 offset:17088
	ds_read_b64 v[64:65], v149 offset:18496
	v_mul_f32_e32 v120, v12, v52
	v_mul_f32_e32 v121, v16, v52
	v_mul_f32_e32 v122, v12, v56
	v_mul_f32_e32 v123, v16, v56
	v_fmac_f32_e32 v120, v13, v53
	v_fmac_f32_e32 v121, v17, v53
	v_fmac_f32_e32 v122, v13, v57
	v_fmac_f32_e32 v123, v17, v57
	v_fmac_f32_e32 v120, v14, v54
	v_fmac_f32_e32 v121, v18, v54
	v_fmac_f32_e32 v122, v14, v58
	v_fmac_f32_e32 v123, v18, v58
	v_fmac_f32_e32 v120, v15, v55
	v_fmac_f32_e32 v121, v19, v55
	v_fmac_f32_e32 v122, v15, v59
	v_fmac_f32_e32 v123, v19, v59
	v_cndmask_b32_e64 v124, v120, v121, s[42:43]
	v_cndmask_b32_e64 v126, v122, v123, s[42:43]
	v_cndmask_b32_e64 v125, v121, v120, s[42:43]
	v_cndmask_b32_e64 v127, v123, v122, s[42:43]
	v_add_f32_dpp v124, v124, v125 quad_perm:[1,0,3,2] row_mask:0xf bank_mask:0xf bound_ctrl:1
	v_add_f32_dpp v126, v126, v127 quad_perm:[1,0,3,2] row_mask:0xf bank_mask:0xf bound_ctrl:1
	v_cndmask_b32_e64 v128, v124, v126, s[44:45]
	v_cndmask_b32_e64 v129, v126, v124, s[44:45]
	v_pk_mul_f32 v[136:137], v[44:45], v[62:63] op_sel_hi:[1,0]
	v_add_f32_dpp v130, v128, v129 quad_perm:[2,3,0,1] row_mask:0xf bank_mask:0xf bound_ctrl:1
	v_pk_mul_f32 v[138:139], v[46:47], v[62:63] op_sel_hi:[1,0]
	v_pk_mul_f32 v[140:141], v[44:45], v[62:63] op_sel:[0,1]
	v_add_f32_dpp v130, v130, v130 row_ror:4 row_mask:0xf bank_mask:0xf bound_ctrl:1
	v_pk_mul_f32 v[142:143], v[46:47], v[62:63] op_sel:[0,1]
	v_cndmask_b32_e64 v145, v63, v62, s[42:43]
	v_add_f32_dpp v130, v130, v130 row_ror:8 row_mask:0xf bank_mask:0xf bound_ctrl:1
	v_cndmask_b32_e32 v2, v2, v146, vcc
	s_nop 0
	v_mov_b32_dpp v132, v130 quad_perm:[0,0,0,0] row_mask:0xf bank_mask:0xf bound_ctrl:1
	v_mov_b32_dpp v134, v130 quad_perm:[1,1,1,1] row_mask:0xf bank_mask:0xf bound_ctrl:1
	v_pk_fma_f32 v[136:137], v[48:49], v[132:133], v[136:137] op_sel_hi:[1,0,1]
	v_pk_fma_f32 v[138:139], v[50:51], v[132:133], v[138:139] op_sel_hi:[1,0,1]
	v_pk_fma_f32 v[140:141], v[48:49], v[134:135], v[140:141] op_sel_hi:[1,0,1]
	v_pk_fma_f32 v[142:143], v[50:51], v[134:135], v[142:143] op_sel_hi:[1,0,1]
	v_cndmask_b32_e64 v144, v134, v132, s[42:43]
	v_pk_fma_f32 v[12:13], v[12:13], v[40:41], v[136:137]
	v_pk_fma_f32 v[14:15], v[14:15], v[42:43], v[138:139]
	v_fma_f32 v150, v145, v67, v130
	v_pk_fma_f32 v[16:17], v[16:17], v[40:41], v[140:141]
	v_pk_fma_f32 v[18:19], v[18:19], v[42:43], v[142:143]
	v_fmac_f32_e32 v150, v144, v66
	s_waitcnt lgkmcnt(0)
	ds_read_b128 v[52:55], v147 offset:19280
	ds_read_b128 v[56:59], v147 offset:19536
	ds_read_b128 v[44:47], v147 offset:18768
	ds_read_b64 v[62:63], v148 offset:19792
	ds_read_b128 v[48:51], v147 offset:19024
	ds_read_b128 v[40:43], v147 offset:18512
	ds_read_b64 v[66:67], v149 offset:19920
	v_mul_f32_e32 v120, v12, v32
	v_mul_f32_e32 v121, v16, v32
	v_mul_f32_e32 v122, v12, v36
	v_mul_f32_e32 v123, v16, v36
	v_fmac_f32_e32 v120, v13, v33
	v_fmac_f32_e32 v121, v17, v33
	v_fmac_f32_e32 v122, v13, v37
	v_fmac_f32_e32 v123, v17, v37
	v_fmac_f32_e32 v120, v14, v34
	v_fmac_f32_e32 v121, v18, v34
	v_fmac_f32_e32 v122, v14, v38
	v_fmac_f32_e32 v123, v18, v38
	v_fmac_f32_e32 v120, v15, v35
	v_fmac_f32_e32 v121, v19, v35
	v_fmac_f32_e32 v122, v15, v39
	v_fmac_f32_e32 v123, v19, v39
	v_cndmask_b32_e64 v124, v120, v121, s[42:43]
	v_cndmask_b32_e64 v126, v122, v123, s[42:43]
	v_cndmask_b32_e64 v125, v121, v120, s[42:43]
	v_cndmask_b32_e64 v127, v123, v122, s[42:43]
	v_add_f32_dpp v124, v124, v125 quad_perm:[1,0,3,2] row_mask:0xf bank_mask:0xf bound_ctrl:1
	v_add_f32_dpp v126, v126, v127 quad_perm:[1,0,3,2] row_mask:0xf bank_mask:0xf bound_ctrl:1
	v_cndmask_b32_e64 v128, v124, v126, s[44:45]
	v_cndmask_b32_e64 v129, v126, v124, s[44:45]
	v_pk_mul_f32 v[136:137], v[24:25], v[60:61] op_sel_hi:[1,0]
	v_add_f32_dpp v130, v128, v129 quad_perm:[2,3,0,1] row_mask:0xf bank_mask:0xf bound_ctrl:1
	v_pk_mul_f32 v[138:139], v[26:27], v[60:61] op_sel_hi:[1,0]
	v_pk_mul_f32 v[140:141], v[24:25], v[60:61] op_sel:[0,1]
	v_add_f32_dpp v130, v130, v130 row_ror:4 row_mask:0xf bank_mask:0xf bound_ctrl:1
	v_pk_mul_f32 v[142:143], v[26:27], v[60:61] op_sel:[0,1]
	v_cndmask_b32_e64 v145, v61, v60, s[42:43]
	v_add_f32_dpp v130, v130, v130 row_ror:8 row_mask:0xf bank_mask:0xf bound_ctrl:1
	v_cndmask_b32_e32 v3, v3, v150, vcc
	v_cmp_eq_u32_e32 vcc, 3, v119
	v_mov_b32_dpp v132, v130 quad_perm:[0,0,0,0] row_mask:0xf bank_mask:0xf bound_ctrl:1
	v_mov_b32_dpp v134, v130 quad_perm:[1,1,1,1] row_mask:0xf bank_mask:0xf bound_ctrl:1
	v_pk_fma_f32 v[136:137], v[28:29], v[132:133], v[136:137] op_sel_hi:[1,0,1]
	v_pk_fma_f32 v[138:139], v[30:31], v[132:133], v[138:139] op_sel_hi:[1,0,1]
	v_pk_fma_f32 v[140:141], v[28:29], v[134:135], v[140:141] op_sel_hi:[1,0,1]
	v_pk_fma_f32 v[142:143], v[30:31], v[134:135], v[142:143] op_sel_hi:[1,0,1]
	v_cndmask_b32_e64 v144, v134, v132, s[42:43]
	v_pk_fma_f32 v[12:13], v[12:13], v[20:21], v[136:137]
	v_pk_fma_f32 v[14:15], v[14:15], v[22:23], v[138:139]
	v_fma_f32 v146, v145, v65, v130
	v_pk_fma_f32 v[16:17], v[16:17], v[20:21], v[140:141]
	v_pk_fma_f32 v[18:19], v[18:19], v[22:23], v[142:143]
	v_fmac_f32_e32 v146, v144, v64
	s_waitcnt lgkmcnt(0)
	ds_read_b128 v[32:35], v147 offset:20704
	ds_read_b128 v[36:39], v147 offset:20960
	ds_read_b128 v[24:27], v147 offset:20192
	ds_read_b64 v[60:61], v148 offset:21216
	ds_read_b128 v[28:31], v147 offset:20448
	ds_read_b128 v[20:23], v147 offset:19936
	ds_read_b64 v[64:65], v149 offset:21344
	v_mul_f32_e32 v120, v12, v52
	v_mul_f32_e32 v121, v16, v52
	v_mul_f32_e32 v122, v12, v56
	v_mul_f32_e32 v123, v16, v56
	v_fmac_f32_e32 v120, v13, v53
	v_fmac_f32_e32 v121, v17, v53
	v_fmac_f32_e32 v122, v13, v57
	v_fmac_f32_e32 v123, v17, v57
	v_fmac_f32_e32 v120, v14, v54
	v_fmac_f32_e32 v121, v18, v54
	v_fmac_f32_e32 v122, v14, v58
	v_fmac_f32_e32 v123, v18, v58
	v_fmac_f32_e32 v120, v15, v55
	v_fmac_f32_e32 v121, v19, v55
	v_fmac_f32_e32 v122, v15, v59
	v_fmac_f32_e32 v123, v19, v59
	v_cndmask_b32_e64 v124, v120, v121, s[42:43]
	v_cndmask_b32_e64 v126, v122, v123, s[42:43]
	v_cndmask_b32_e64 v125, v121, v120, s[42:43]
	v_cndmask_b32_e64 v127, v123, v122, s[42:43]
	v_add_f32_dpp v124, v124, v125 quad_perm:[1,0,3,2] row_mask:0xf bank_mask:0xf bound_ctrl:1
	v_add_f32_dpp v126, v126, v127 quad_perm:[1,0,3,2] row_mask:0xf bank_mask:0xf bound_ctrl:1
	v_cndmask_b32_e64 v128, v124, v126, s[44:45]
	v_cndmask_b32_e64 v129, v126, v124, s[44:45]
	v_pk_mul_f32 v[136:137], v[44:45], v[62:63] op_sel_hi:[1,0]
	v_add_f32_dpp v130, v128, v129 quad_perm:[2,3,0,1] row_mask:0xf bank_mask:0xf bound_ctrl:1
	v_pk_mul_f32 v[138:139], v[46:47], v[62:63] op_sel_hi:[1,0]
	v_pk_mul_f32 v[140:141], v[44:45], v[62:63] op_sel:[0,1]
	v_add_f32_dpp v130, v130, v130 row_ror:4 row_mask:0xf bank_mask:0xf bound_ctrl:1
	v_pk_mul_f32 v[142:143], v[46:47], v[62:63] op_sel:[0,1]
	v_cndmask_b32_e64 v145, v63, v62, s[42:43]
	v_add_f32_dpp v130, v130, v130 row_ror:8 row_mask:0xf bank_mask:0xf bound_ctrl:1
	v_cndmask_b32_e32 v0, v0, v146, vcc
	s_nop 0
	v_mov_b32_dpp v132, v130 quad_perm:[0,0,0,0] row_mask:0xf bank_mask:0xf bound_ctrl:1
	v_mov_b32_dpp v134, v130 quad_perm:[1,1,1,1] row_mask:0xf bank_mask:0xf bound_ctrl:1
	v_pk_fma_f32 v[136:137], v[48:49], v[132:133], v[136:137] op_sel_hi:[1,0,1]
	v_pk_fma_f32 v[138:139], v[50:51], v[132:133], v[138:139] op_sel_hi:[1,0,1]
	v_pk_fma_f32 v[140:141], v[48:49], v[134:135], v[140:141] op_sel_hi:[1,0,1]
	v_pk_fma_f32 v[142:143], v[50:51], v[134:135], v[142:143] op_sel_hi:[1,0,1]
	v_cndmask_b32_e64 v144, v134, v132, s[42:43]
	v_pk_fma_f32 v[12:13], v[12:13], v[40:41], v[136:137]
	v_pk_fma_f32 v[14:15], v[14:15], v[42:43], v[138:139]
	v_fma_f32 v150, v145, v67, v130
	v_pk_fma_f32 v[16:17], v[16:17], v[40:41], v[140:141]
	v_pk_fma_f32 v[18:19], v[18:19], v[42:43], v[142:143]
	v_fmac_f32_e32 v150, v144, v66
	s_waitcnt lgkmcnt(0)
	ds_read_b128 v[52:55], v147 offset:22128
	ds_read_b128 v[56:59], v147 offset:22384
	ds_read_b128 v[44:47], v147 offset:21616
	ds_read_b64 v[62:63], v148 offset:22640
	ds_read_b128 v[48:51], v147 offset:21872
	ds_read_b128 v[40:43], v147 offset:21360
	ds_read_b64 v[66:67], v149 offset:22768
	v_mul_f32_e32 v120, v12, v32
	v_mul_f32_e32 v121, v16, v32
	v_mul_f32_e32 v122, v12, v36
	v_mul_f32_e32 v123, v16, v36
	v_fmac_f32_e32 v120, v13, v33
	v_fmac_f32_e32 v121, v17, v33
	v_fmac_f32_e32 v122, v13, v37
	v_fmac_f32_e32 v123, v17, v37
	v_fmac_f32_e32 v120, v14, v34
	v_fmac_f32_e32 v121, v18, v34
	v_fmac_f32_e32 v122, v14, v38
	v_fmac_f32_e32 v123, v18, v38
	v_fmac_f32_e32 v120, v15, v35
	v_fmac_f32_e32 v121, v19, v35
	v_fmac_f32_e32 v122, v15, v39
	v_fmac_f32_e32 v123, v19, v39
	v_cndmask_b32_e64 v124, v120, v121, s[42:43]
	v_cndmask_b32_e64 v126, v122, v123, s[42:43]
	v_cndmask_b32_e64 v125, v121, v120, s[42:43]
	v_cndmask_b32_e64 v127, v123, v122, s[42:43]
	v_add_f32_dpp v124, v124, v125 quad_perm:[1,0,3,2] row_mask:0xf bank_mask:0xf bound_ctrl:1
	v_add_f32_dpp v126, v126, v127 quad_perm:[1,0,3,2] row_mask:0xf bank_mask:0xf bound_ctrl:1
	v_cndmask_b32_e64 v128, v124, v126, s[44:45]
	v_cndmask_b32_e64 v129, v126, v124, s[44:45]
	v_pk_mul_f32 v[136:137], v[24:25], v[60:61] op_sel_hi:[1,0]
	v_add_f32_dpp v130, v128, v129 quad_perm:[2,3,0,1] row_mask:0xf bank_mask:0xf bound_ctrl:1
	v_pk_mul_f32 v[138:139], v[26:27], v[60:61] op_sel_hi:[1,0]
	v_pk_mul_f32 v[140:141], v[24:25], v[60:61] op_sel:[0,1]
	v_add_f32_dpp v130, v130, v130 row_ror:4 row_mask:0xf bank_mask:0xf bound_ctrl:1
	v_pk_mul_f32 v[142:143], v[26:27], v[60:61] op_sel:[0,1]
	v_cndmask_b32_e64 v145, v61, v60, s[42:43]
	v_add_f32_dpp v130, v130, v130 row_ror:8 row_mask:0xf bank_mask:0xf bound_ctrl:1
	v_cndmask_b32_e32 v1, v1, v150, vcc
	s_nop 0
	v_mov_b32_dpp v132, v130 quad_perm:[0,0,0,0] row_mask:0xf bank_mask:0xf bound_ctrl:1
	v_mov_b32_dpp v134, v130 quad_perm:[1,1,1,1] row_mask:0xf bank_mask:0xf bound_ctrl:1
	v_pk_fma_f32 v[136:137], v[28:29], v[132:133], v[136:137] op_sel_hi:[1,0,1]
	v_pk_fma_f32 v[138:139], v[30:31], v[132:133], v[138:139] op_sel_hi:[1,0,1]
	v_pk_fma_f32 v[140:141], v[28:29], v[134:135], v[140:141] op_sel_hi:[1,0,1]
	v_pk_fma_f32 v[142:143], v[30:31], v[134:135], v[142:143] op_sel_hi:[1,0,1]
	v_cndmask_b32_e64 v144, v134, v132, s[42:43]
	v_pk_fma_f32 v[12:13], v[12:13], v[20:21], v[136:137]
	v_pk_fma_f32 v[14:15], v[14:15], v[22:23], v[138:139]
	v_fma_f32 v146, v145, v65, v130
	v_pk_fma_f32 v[16:17], v[16:17], v[20:21], v[140:141]
	v_pk_fma_f32 v[18:19], v[18:19], v[22:23], v[142:143]
	v_fmac_f32_e32 v146, v144, v64
	s_waitcnt lgkmcnt(0)
	ds_read_b128 v[32:35], v147 offset:23552
	ds_read_b128 v[36:39], v147 offset:23808
	ds_read_b128 v[24:27], v147 offset:23040
	ds_read_b64 v[60:61], v148 offset:24064
	ds_read_b128 v[28:31], v147 offset:23296
	ds_read_b128 v[20:23], v147 offset:22784
	ds_read_b64 v[64:65], v149 offset:24192
	v_mul_f32_e32 v120, v12, v52
	v_mul_f32_e32 v121, v16, v52
	v_mul_f32_e32 v122, v12, v56
	v_mul_f32_e32 v123, v16, v56
	v_fmac_f32_e32 v120, v13, v53
	v_fmac_f32_e32 v121, v17, v53
	v_fmac_f32_e32 v122, v13, v57
	v_fmac_f32_e32 v123, v17, v57
	v_fmac_f32_e32 v120, v14, v54
	v_fmac_f32_e32 v121, v18, v54
	v_fmac_f32_e32 v122, v14, v58
	v_fmac_f32_e32 v123, v18, v58
	v_fmac_f32_e32 v120, v15, v55
	v_fmac_f32_e32 v121, v19, v55
	v_fmac_f32_e32 v122, v15, v59
	v_fmac_f32_e32 v123, v19, v59
	v_cndmask_b32_e64 v124, v120, v121, s[42:43]
	v_cndmask_b32_e64 v126, v122, v123, s[42:43]
	v_cndmask_b32_e64 v125, v121, v120, s[42:43]
	v_cndmask_b32_e64 v127, v123, v122, s[42:43]
	v_add_f32_dpp v124, v124, v125 quad_perm:[1,0,3,2] row_mask:0xf bank_mask:0xf bound_ctrl:1
	v_add_f32_dpp v126, v126, v127 quad_perm:[1,0,3,2] row_mask:0xf bank_mask:0xf bound_ctrl:1
	v_cndmask_b32_e64 v128, v124, v126, s[44:45]
	v_cndmask_b32_e64 v129, v126, v124, s[44:45]
	v_pk_mul_f32 v[136:137], v[44:45], v[62:63] op_sel_hi:[1,0]
	v_add_f32_dpp v130, v128, v129 quad_perm:[2,3,0,1] row_mask:0xf bank_mask:0xf bound_ctrl:1
	v_pk_mul_f32 v[138:139], v[46:47], v[62:63] op_sel_hi:[1,0]
	v_pk_mul_f32 v[140:141], v[44:45], v[62:63] op_sel:[0,1]
	v_add_f32_dpp v130, v130, v130 row_ror:4 row_mask:0xf bank_mask:0xf bound_ctrl:1
	v_pk_mul_f32 v[142:143], v[46:47], v[62:63] op_sel:[0,1]
	v_cndmask_b32_e64 v145, v63, v62, s[42:43]
	v_add_f32_dpp v130, v130, v130 row_ror:8 row_mask:0xf bank_mask:0xf bound_ctrl:1
	v_cndmask_b32_e32 v2, v2, v146, vcc
	s_nop 0
	v_mov_b32_dpp v132, v130 quad_perm:[0,0,0,0] row_mask:0xf bank_mask:0xf bound_ctrl:1
	v_mov_b32_dpp v134, v130 quad_perm:[1,1,1,1] row_mask:0xf bank_mask:0xf bound_ctrl:1
	v_pk_fma_f32 v[136:137], v[48:49], v[132:133], v[136:137] op_sel_hi:[1,0,1]
	v_pk_fma_f32 v[138:139], v[50:51], v[132:133], v[138:139] op_sel_hi:[1,0,1]
	v_pk_fma_f32 v[140:141], v[48:49], v[134:135], v[140:141] op_sel_hi:[1,0,1]
	v_pk_fma_f32 v[142:143], v[50:51], v[134:135], v[142:143] op_sel_hi:[1,0,1]
	v_cndmask_b32_e64 v144, v134, v132, s[42:43]
	v_pk_fma_f32 v[12:13], v[12:13], v[40:41], v[136:137]
	v_pk_fma_f32 v[14:15], v[14:15], v[42:43], v[138:139]
	v_fma_f32 v150, v145, v67, v130
	v_pk_fma_f32 v[16:17], v[16:17], v[40:41], v[140:141]
	v_pk_fma_f32 v[18:19], v[18:19], v[42:43], v[142:143]
	v_fmac_f32_e32 v150, v144, v66
	s_waitcnt lgkmcnt(0)
	ds_read_b128 v[52:55], v147 offset:24976
	ds_read_b128 v[56:59], v147 offset:25232
	ds_read_b128 v[44:47], v147 offset:24464
	ds_read_b64 v[62:63], v148 offset:25488
	ds_read_b128 v[48:51], v147 offset:24720
	ds_read_b128 v[40:43], v147 offset:24208
	ds_read_b64 v[66:67], v149 offset:25616
	v_mul_f32_e32 v120, v12, v32
	v_mul_f32_e32 v121, v16, v32
	v_mul_f32_e32 v122, v12, v36
	v_mul_f32_e32 v123, v16, v36
	v_fmac_f32_e32 v120, v13, v33
	v_fmac_f32_e32 v121, v17, v33
	v_fmac_f32_e32 v122, v13, v37
	v_fmac_f32_e32 v123, v17, v37
	v_fmac_f32_e32 v120, v14, v34
	v_fmac_f32_e32 v121, v18, v34
	v_fmac_f32_e32 v122, v14, v38
	v_fmac_f32_e32 v123, v18, v38
	v_fmac_f32_e32 v120, v15, v35
	v_fmac_f32_e32 v121, v19, v35
	v_fmac_f32_e32 v122, v15, v39
	v_fmac_f32_e32 v123, v19, v39
	v_cndmask_b32_e64 v124, v120, v121, s[42:43]
	v_cndmask_b32_e64 v126, v122, v123, s[42:43]
	v_cndmask_b32_e64 v125, v121, v120, s[42:43]
	v_cndmask_b32_e64 v127, v123, v122, s[42:43]
	v_add_f32_dpp v124, v124, v125 quad_perm:[1,0,3,2] row_mask:0xf bank_mask:0xf bound_ctrl:1
	v_add_f32_dpp v126, v126, v127 quad_perm:[1,0,3,2] row_mask:0xf bank_mask:0xf bound_ctrl:1
	v_cndmask_b32_e64 v128, v124, v126, s[44:45]
	v_cndmask_b32_e64 v129, v126, v124, s[44:45]
	v_pk_mul_f32 v[136:137], v[24:25], v[60:61] op_sel_hi:[1,0]
	v_add_f32_dpp v130, v128, v129 quad_perm:[2,3,0,1] row_mask:0xf bank_mask:0xf bound_ctrl:1
	v_pk_mul_f32 v[138:139], v[26:27], v[60:61] op_sel_hi:[1,0]
	v_pk_mul_f32 v[140:141], v[24:25], v[60:61] op_sel:[0,1]
	v_add_f32_dpp v130, v130, v130 row_ror:4 row_mask:0xf bank_mask:0xf bound_ctrl:1
	v_pk_mul_f32 v[142:143], v[26:27], v[60:61] op_sel:[0,1]
	v_cndmask_b32_e64 v145, v61, v60, s[42:43]
	v_add_f32_dpp v130, v130, v130 row_ror:8 row_mask:0xf bank_mask:0xf bound_ctrl:1
	v_cndmask_b32_e32 v3, v3, v150, vcc
	v_cmp_eq_u32_e32 vcc, 0, v119
	v_mov_b32_dpp v132, v130 quad_perm:[0,0,0,0] row_mask:0xf bank_mask:0xf bound_ctrl:1
	v_mov_b32_dpp v134, v130 quad_perm:[1,1,1,1] row_mask:0xf bank_mask:0xf bound_ctrl:1
	v_pk_fma_f32 v[136:137], v[28:29], v[132:133], v[136:137] op_sel_hi:[1,0,1]
	v_pk_fma_f32 v[138:139], v[30:31], v[132:133], v[138:139] op_sel_hi:[1,0,1]
	v_pk_fma_f32 v[140:141], v[28:29], v[134:135], v[140:141] op_sel_hi:[1,0,1]
	v_pk_fma_f32 v[142:143], v[30:31], v[134:135], v[142:143] op_sel_hi:[1,0,1]
	v_cndmask_b32_e64 v144, v134, v132, s[42:43]
	v_pk_fma_f32 v[12:13], v[12:13], v[20:21], v[136:137]
	v_pk_fma_f32 v[14:15], v[14:15], v[22:23], v[138:139]
	v_fma_f32 v146, v145, v65, v130
	v_pk_fma_f32 v[16:17], v[16:17], v[20:21], v[140:141]
	v_pk_fma_f32 v[18:19], v[18:19], v[22:23], v[142:143]
	v_fmac_f32_e32 v146, v144, v64
	s_waitcnt lgkmcnt(0)
	ds_read_b128 v[32:35], v147 offset:26400
	ds_read_b128 v[36:39], v147 offset:26656
	ds_read_b128 v[24:27], v147 offset:25888
	ds_read_b64 v[60:61], v148 offset:26912
	ds_read_b128 v[28:31], v147 offset:26144
	ds_read_b128 v[20:23], v147 offset:25632
	ds_read_b64 v[64:65], v149 offset:27040
	v_mul_f32_e32 v120, v12, v52
	v_mul_f32_e32 v121, v16, v52
	v_mul_f32_e32 v122, v12, v56
	v_mul_f32_e32 v123, v16, v56
	v_fmac_f32_e32 v120, v13, v53
	v_fmac_f32_e32 v121, v17, v53
	v_fmac_f32_e32 v122, v13, v57
	v_fmac_f32_e32 v123, v17, v57
	v_fmac_f32_e32 v120, v14, v54
	v_fmac_f32_e32 v121, v18, v54
	v_fmac_f32_e32 v122, v14, v58
	v_fmac_f32_e32 v123, v18, v58
	v_fmac_f32_e32 v120, v15, v55
	v_fmac_f32_e32 v121, v19, v55
	v_fmac_f32_e32 v122, v15, v59
	v_fmac_f32_e32 v123, v19, v59
	v_cndmask_b32_e64 v124, v120, v121, s[42:43]
	v_cndmask_b32_e64 v126, v122, v123, s[42:43]
	v_cndmask_b32_e64 v125, v121, v120, s[42:43]
	v_cndmask_b32_e64 v127, v123, v122, s[42:43]
	v_add_f32_dpp v124, v124, v125 quad_perm:[1,0,3,2] row_mask:0xf bank_mask:0xf bound_ctrl:1
	v_add_f32_dpp v126, v126, v127 quad_perm:[1,0,3,2] row_mask:0xf bank_mask:0xf bound_ctrl:1
	v_cndmask_b32_e64 v128, v124, v126, s[44:45]
	v_cndmask_b32_e64 v129, v126, v124, s[44:45]
	v_pk_mul_f32 v[136:137], v[44:45], v[62:63] op_sel_hi:[1,0]
	v_add_f32_dpp v130, v128, v129 quad_perm:[2,3,0,1] row_mask:0xf bank_mask:0xf bound_ctrl:1
	v_pk_mul_f32 v[138:139], v[46:47], v[62:63] op_sel_hi:[1,0]
	v_pk_mul_f32 v[140:141], v[44:45], v[62:63] op_sel:[0,1]
	v_add_f32_dpp v130, v130, v130 row_ror:4 row_mask:0xf bank_mask:0xf bound_ctrl:1
	v_pk_mul_f32 v[142:143], v[46:47], v[62:63] op_sel:[0,1]
	v_cndmask_b32_e64 v145, v63, v62, s[42:43]
	v_add_f32_dpp v130, v130, v130 row_ror:8 row_mask:0xf bank_mask:0xf bound_ctrl:1
	v_cndmask_b32_e32 v4, v4, v146, vcc
	s_nop 0
	v_mov_b32_dpp v132, v130 quad_perm:[0,0,0,0] row_mask:0xf bank_mask:0xf bound_ctrl:1
	v_mov_b32_dpp v134, v130 quad_perm:[1,1,1,1] row_mask:0xf bank_mask:0xf bound_ctrl:1
	v_pk_fma_f32 v[136:137], v[48:49], v[132:133], v[136:137] op_sel_hi:[1,0,1]
	v_pk_fma_f32 v[138:139], v[50:51], v[132:133], v[138:139] op_sel_hi:[1,0,1]
	v_pk_fma_f32 v[140:141], v[48:49], v[134:135], v[140:141] op_sel_hi:[1,0,1]
	v_pk_fma_f32 v[142:143], v[50:51], v[134:135], v[142:143] op_sel_hi:[1,0,1]
	v_cndmask_b32_e64 v144, v134, v132, s[42:43]
	v_pk_fma_f32 v[12:13], v[12:13], v[40:41], v[136:137]
	v_pk_fma_f32 v[14:15], v[14:15], v[42:43], v[138:139]
	v_fma_f32 v150, v145, v67, v130
	v_pk_fma_f32 v[16:17], v[16:17], v[40:41], v[140:141]
	v_pk_fma_f32 v[18:19], v[18:19], v[42:43], v[142:143]
	v_fmac_f32_e32 v150, v144, v66
	s_waitcnt lgkmcnt(0)
	ds_read_b128 v[52:55], v147 offset:27824
	ds_read_b128 v[56:59], v147 offset:28080
	ds_read_b128 v[44:47], v147 offset:27312
	ds_read_b64 v[62:63], v148 offset:28336
	ds_read_b128 v[48:51], v147 offset:27568
	ds_read_b128 v[40:43], v147 offset:27056
	ds_read_b64 v[66:67], v149 offset:28464
	v_mul_f32_e32 v120, v12, v32
	v_mul_f32_e32 v121, v16, v32
	v_mul_f32_e32 v122, v12, v36
	v_mul_f32_e32 v123, v16, v36
	v_fmac_f32_e32 v120, v13, v33
	v_fmac_f32_e32 v121, v17, v33
	v_fmac_f32_e32 v122, v13, v37
	v_fmac_f32_e32 v123, v17, v37
	v_fmac_f32_e32 v120, v14, v34
	v_fmac_f32_e32 v121, v18, v34
	v_fmac_f32_e32 v122, v14, v38
	v_fmac_f32_e32 v123, v18, v38
	v_fmac_f32_e32 v120, v15, v35
	v_fmac_f32_e32 v121, v19, v35
	v_fmac_f32_e32 v122, v15, v39
	v_fmac_f32_e32 v123, v19, v39
	v_cndmask_b32_e64 v124, v120, v121, s[42:43]
	v_cndmask_b32_e64 v126, v122, v123, s[42:43]
	v_cndmask_b32_e64 v125, v121, v120, s[42:43]
	v_cndmask_b32_e64 v127, v123, v122, s[42:43]
	v_add_f32_dpp v124, v124, v125 quad_perm:[1,0,3,2] row_mask:0xf bank_mask:0xf bound_ctrl:1
	v_add_f32_dpp v126, v126, v127 quad_perm:[1,0,3,2] row_mask:0xf bank_mask:0xf bound_ctrl:1
	v_cndmask_b32_e64 v128, v124, v126, s[44:45]
	v_cndmask_b32_e64 v129, v126, v124, s[44:45]
	v_pk_mul_f32 v[136:137], v[24:25], v[60:61] op_sel_hi:[1,0]
	v_add_f32_dpp v130, v128, v129 quad_perm:[2,3,0,1] row_mask:0xf bank_mask:0xf bound_ctrl:1
	v_pk_mul_f32 v[138:139], v[26:27], v[60:61] op_sel_hi:[1,0]
	v_pk_mul_f32 v[140:141], v[24:25], v[60:61] op_sel:[0,1]
	v_add_f32_dpp v130, v130, v130 row_ror:4 row_mask:0xf bank_mask:0xf bound_ctrl:1
	v_pk_mul_f32 v[142:143], v[26:27], v[60:61] op_sel:[0,1]
	v_cndmask_b32_e64 v145, v61, v60, s[42:43]
	v_add_f32_dpp v130, v130, v130 row_ror:8 row_mask:0xf bank_mask:0xf bound_ctrl:1
	v_cndmask_b32_e32 v5, v5, v150, vcc
	s_nop 0
	v_mov_b32_dpp v132, v130 quad_perm:[0,0,0,0] row_mask:0xf bank_mask:0xf bound_ctrl:1
	v_mov_b32_dpp v134, v130 quad_perm:[1,1,1,1] row_mask:0xf bank_mask:0xf bound_ctrl:1
	v_pk_fma_f32 v[136:137], v[28:29], v[132:133], v[136:137] op_sel_hi:[1,0,1]
	v_pk_fma_f32 v[138:139], v[30:31], v[132:133], v[138:139] op_sel_hi:[1,0,1]
	v_pk_fma_f32 v[140:141], v[28:29], v[134:135], v[140:141] op_sel_hi:[1,0,1]
	v_pk_fma_f32 v[142:143], v[30:31], v[134:135], v[142:143] op_sel_hi:[1,0,1]
	v_cndmask_b32_e64 v144, v134, v132, s[42:43]
	v_pk_fma_f32 v[12:13], v[12:13], v[20:21], v[136:137]
	v_pk_fma_f32 v[14:15], v[14:15], v[22:23], v[138:139]
	v_fma_f32 v146, v145, v65, v130
	v_pk_fma_f32 v[16:17], v[16:17], v[20:21], v[140:141]
	v_pk_fma_f32 v[18:19], v[18:19], v[22:23], v[142:143]
	v_fmac_f32_e32 v146, v144, v64
	s_waitcnt lgkmcnt(0)
	ds_read_b128 v[32:35], v147 offset:29248
	ds_read_b128 v[36:39], v147 offset:29504
	ds_read_b128 v[24:27], v147 offset:28736
	ds_read_b64 v[60:61], v148 offset:29760
	ds_read_b128 v[28:31], v147 offset:28992
	ds_read_b128 v[20:23], v147 offset:28480
	ds_read_b64 v[64:65], v149 offset:29888
	v_mul_f32_e32 v120, v12, v52
	v_mul_f32_e32 v121, v16, v52
	v_mul_f32_e32 v122, v12, v56
	v_mul_f32_e32 v123, v16, v56
	v_fmac_f32_e32 v120, v13, v53
	v_fmac_f32_e32 v121, v17, v53
	v_fmac_f32_e32 v122, v13, v57
	v_fmac_f32_e32 v123, v17, v57
	v_fmac_f32_e32 v120, v14, v54
	v_fmac_f32_e32 v121, v18, v54
	v_fmac_f32_e32 v122, v14, v58
	v_fmac_f32_e32 v123, v18, v58
	v_fmac_f32_e32 v120, v15, v55
	v_fmac_f32_e32 v121, v19, v55
	v_fmac_f32_e32 v122, v15, v59
	v_fmac_f32_e32 v123, v19, v59
	v_cndmask_b32_e64 v124, v120, v121, s[42:43]
	v_cndmask_b32_e64 v126, v122, v123, s[42:43]
	v_cndmask_b32_e64 v125, v121, v120, s[42:43]
	v_cndmask_b32_e64 v127, v123, v122, s[42:43]
	v_add_f32_dpp v124, v124, v125 quad_perm:[1,0,3,2] row_mask:0xf bank_mask:0xf bound_ctrl:1
	v_add_f32_dpp v126, v126, v127 quad_perm:[1,0,3,2] row_mask:0xf bank_mask:0xf bound_ctrl:1
	v_cndmask_b32_e64 v128, v124, v126, s[44:45]
	v_cndmask_b32_e64 v129, v126, v124, s[44:45]
	v_pk_mul_f32 v[136:137], v[44:45], v[62:63] op_sel_hi:[1,0]
	v_add_f32_dpp v130, v128, v129 quad_perm:[2,3,0,1] row_mask:0xf bank_mask:0xf bound_ctrl:1
	v_pk_mul_f32 v[138:139], v[46:47], v[62:63] op_sel_hi:[1,0]
	v_pk_mul_f32 v[140:141], v[44:45], v[62:63] op_sel:[0,1]
	v_add_f32_dpp v130, v130, v130 row_ror:4 row_mask:0xf bank_mask:0xf bound_ctrl:1
	v_pk_mul_f32 v[142:143], v[46:47], v[62:63] op_sel:[0,1]
	v_cndmask_b32_e64 v145, v63, v62, s[42:43]
	v_add_f32_dpp v130, v130, v130 row_ror:8 row_mask:0xf bank_mask:0xf bound_ctrl:1
	v_cndmask_b32_e32 v6, v6, v146, vcc
	s_nop 0
	v_mov_b32_dpp v132, v130 quad_perm:[0,0,0,0] row_mask:0xf bank_mask:0xf bound_ctrl:1
	v_mov_b32_dpp v134, v130 quad_perm:[1,1,1,1] row_mask:0xf bank_mask:0xf bound_ctrl:1
	v_pk_fma_f32 v[136:137], v[48:49], v[132:133], v[136:137] op_sel_hi:[1,0,1]
	v_pk_fma_f32 v[138:139], v[50:51], v[132:133], v[138:139] op_sel_hi:[1,0,1]
	v_pk_fma_f32 v[140:141], v[48:49], v[134:135], v[140:141] op_sel_hi:[1,0,1]
	v_pk_fma_f32 v[142:143], v[50:51], v[134:135], v[142:143] op_sel_hi:[1,0,1]
	v_cndmask_b32_e64 v144, v134, v132, s[42:43]
	v_pk_fma_f32 v[12:13], v[12:13], v[40:41], v[136:137]
	v_pk_fma_f32 v[14:15], v[14:15], v[42:43], v[138:139]
	v_fma_f32 v150, v145, v67, v130
	v_pk_fma_f32 v[16:17], v[16:17], v[40:41], v[140:141]
	v_pk_fma_f32 v[18:19], v[18:19], v[42:43], v[142:143]
	v_fmac_f32_e32 v150, v144, v66
	s_waitcnt lgkmcnt(0)
	ds_read_b128 v[52:55], v147 offset:30672
	ds_read_b128 v[56:59], v147 offset:30928
	ds_read_b128 v[44:47], v147 offset:30160
	ds_read_b64 v[62:63], v148 offset:31184
	ds_read_b128 v[48:51], v147 offset:30416
	ds_read_b128 v[40:43], v147 offset:29904
	ds_read_b64 v[66:67], v149 offset:31312
	v_mul_f32_e32 v120, v12, v32
	v_mul_f32_e32 v121, v16, v32
	v_mul_f32_e32 v122, v12, v36
	v_mul_f32_e32 v123, v16, v36
	v_fmac_f32_e32 v120, v13, v33
	v_fmac_f32_e32 v121, v17, v33
	v_fmac_f32_e32 v122, v13, v37
	v_fmac_f32_e32 v123, v17, v37
	v_fmac_f32_e32 v120, v14, v34
	v_fmac_f32_e32 v121, v18, v34
	v_fmac_f32_e32 v122, v14, v38
	v_fmac_f32_e32 v123, v18, v38
	v_fmac_f32_e32 v120, v15, v35
	v_fmac_f32_e32 v121, v19, v35
	v_fmac_f32_e32 v122, v15, v39
	v_fmac_f32_e32 v123, v19, v39
	v_cndmask_b32_e64 v124, v120, v121, s[42:43]
	v_cndmask_b32_e64 v126, v122, v123, s[42:43]
	v_cndmask_b32_e64 v125, v121, v120, s[42:43]
	v_cndmask_b32_e64 v127, v123, v122, s[42:43]
	v_add_f32_dpp v124, v124, v125 quad_perm:[1,0,3,2] row_mask:0xf bank_mask:0xf bound_ctrl:1
	v_add_f32_dpp v126, v126, v127 quad_perm:[1,0,3,2] row_mask:0xf bank_mask:0xf bound_ctrl:1
	v_cndmask_b32_e64 v128, v124, v126, s[44:45]
	v_cndmask_b32_e64 v129, v126, v124, s[44:45]
	v_pk_mul_f32 v[136:137], v[24:25], v[60:61] op_sel_hi:[1,0]
	v_add_f32_dpp v130, v128, v129 quad_perm:[2,3,0,1] row_mask:0xf bank_mask:0xf bound_ctrl:1
	v_pk_mul_f32 v[138:139], v[26:27], v[60:61] op_sel_hi:[1,0]
	v_pk_mul_f32 v[140:141], v[24:25], v[60:61] op_sel:[0,1]
	v_add_f32_dpp v130, v130, v130 row_ror:4 row_mask:0xf bank_mask:0xf bound_ctrl:1
	v_pk_mul_f32 v[142:143], v[26:27], v[60:61] op_sel:[0,1]
	v_cndmask_b32_e64 v145, v61, v60, s[42:43]
	v_add_f32_dpp v130, v130, v130 row_ror:8 row_mask:0xf bank_mask:0xf bound_ctrl:1
	v_cndmask_b32_e32 v7, v7, v150, vcc
	v_cmp_eq_u32_e32 vcc, 1, v119
	v_mov_b32_dpp v132, v130 quad_perm:[0,0,0,0] row_mask:0xf bank_mask:0xf bound_ctrl:1
	v_mov_b32_dpp v134, v130 quad_perm:[1,1,1,1] row_mask:0xf bank_mask:0xf bound_ctrl:1
	v_pk_fma_f32 v[136:137], v[28:29], v[132:133], v[136:137] op_sel_hi:[1,0,1]
	v_pk_fma_f32 v[138:139], v[30:31], v[132:133], v[138:139] op_sel_hi:[1,0,1]
	v_pk_fma_f32 v[140:141], v[28:29], v[134:135], v[140:141] op_sel_hi:[1,0,1]
	v_pk_fma_f32 v[142:143], v[30:31], v[134:135], v[142:143] op_sel_hi:[1,0,1]
	v_cndmask_b32_e64 v144, v134, v132, s[42:43]
	v_pk_fma_f32 v[12:13], v[12:13], v[20:21], v[136:137]
	v_pk_fma_f32 v[14:15], v[14:15], v[22:23], v[138:139]
	v_fma_f32 v146, v145, v65, v130
	v_pk_fma_f32 v[16:17], v[16:17], v[20:21], v[140:141]
	v_pk_fma_f32 v[18:19], v[18:19], v[22:23], v[142:143]
	v_fmac_f32_e32 v146, v144, v64
	s_waitcnt lgkmcnt(0)
	ds_read_b128 v[32:35], v147 offset:32096
	ds_read_b128 v[36:39], v147 offset:32352
	ds_read_b128 v[24:27], v147 offset:31584
	ds_read_b64 v[60:61], v148 offset:32608
	ds_read_b128 v[28:31], v147 offset:31840
	ds_read_b128 v[20:23], v147 offset:31328
	ds_read_b64 v[64:65], v149 offset:32736
	v_mul_f32_e32 v120, v12, v52
	v_mul_f32_e32 v121, v16, v52
	v_mul_f32_e32 v122, v12, v56
	v_mul_f32_e32 v123, v16, v56
	v_fmac_f32_e32 v120, v13, v53
	v_fmac_f32_e32 v121, v17, v53
	v_fmac_f32_e32 v122, v13, v57
	v_fmac_f32_e32 v123, v17, v57
	v_fmac_f32_e32 v120, v14, v54
	v_fmac_f32_e32 v121, v18, v54
	v_fmac_f32_e32 v122, v14, v58
	v_fmac_f32_e32 v123, v18, v58
	v_fmac_f32_e32 v120, v15, v55
	v_fmac_f32_e32 v121, v19, v55
	v_fmac_f32_e32 v122, v15, v59
	v_fmac_f32_e32 v123, v19, v59
	v_cndmask_b32_e64 v124, v120, v121, s[42:43]
	v_cndmask_b32_e64 v126, v122, v123, s[42:43]
	v_cndmask_b32_e64 v125, v121, v120, s[42:43]
	v_cndmask_b32_e64 v127, v123, v122, s[42:43]
	v_add_f32_dpp v124, v124, v125 quad_perm:[1,0,3,2] row_mask:0xf bank_mask:0xf bound_ctrl:1
	v_add_f32_dpp v126, v126, v127 quad_perm:[1,0,3,2] row_mask:0xf bank_mask:0xf bound_ctrl:1
	v_cndmask_b32_e64 v128, v124, v126, s[44:45]
	v_cndmask_b32_e64 v129, v126, v124, s[44:45]
	v_pk_mul_f32 v[136:137], v[44:45], v[62:63] op_sel_hi:[1,0]
	v_add_f32_dpp v130, v128, v129 quad_perm:[2,3,0,1] row_mask:0xf bank_mask:0xf bound_ctrl:1
	v_pk_mul_f32 v[138:139], v[46:47], v[62:63] op_sel_hi:[1,0]
	v_pk_mul_f32 v[140:141], v[44:45], v[62:63] op_sel:[0,1]
	v_add_f32_dpp v130, v130, v130 row_ror:4 row_mask:0xf bank_mask:0xf bound_ctrl:1
	v_pk_mul_f32 v[142:143], v[46:47], v[62:63] op_sel:[0,1]
	v_cndmask_b32_e64 v145, v63, v62, s[42:43]
	v_add_f32_dpp v130, v130, v130 row_ror:8 row_mask:0xf bank_mask:0xf bound_ctrl:1
	v_cndmask_b32_e32 v4, v4, v146, vcc
	s_nop 0
	v_mov_b32_dpp v132, v130 quad_perm:[0,0,0,0] row_mask:0xf bank_mask:0xf bound_ctrl:1
	v_mov_b32_dpp v134, v130 quad_perm:[1,1,1,1] row_mask:0xf bank_mask:0xf bound_ctrl:1
	v_pk_fma_f32 v[136:137], v[48:49], v[132:133], v[136:137] op_sel_hi:[1,0,1]
	v_pk_fma_f32 v[138:139], v[50:51], v[132:133], v[138:139] op_sel_hi:[1,0,1]
	v_pk_fma_f32 v[140:141], v[48:49], v[134:135], v[140:141] op_sel_hi:[1,0,1]
	v_pk_fma_f32 v[142:143], v[50:51], v[134:135], v[142:143] op_sel_hi:[1,0,1]
	v_cndmask_b32_e64 v144, v134, v132, s[42:43]
	v_pk_fma_f32 v[12:13], v[12:13], v[40:41], v[136:137]
	v_pk_fma_f32 v[14:15], v[14:15], v[42:43], v[138:139]
	v_fma_f32 v150, v145, v67, v130
	v_pk_fma_f32 v[16:17], v[16:17], v[40:41], v[140:141]
	v_pk_fma_f32 v[18:19], v[18:19], v[42:43], v[142:143]
	v_fmac_f32_e32 v150, v144, v66
	s_waitcnt lgkmcnt(0)
	ds_read_b128 v[52:55], v147 offset:33520
	ds_read_b128 v[56:59], v147 offset:33776
	ds_read_b128 v[44:47], v147 offset:33008
	ds_read_b64 v[62:63], v148 offset:34032
	ds_read_b128 v[48:51], v147 offset:33264
	ds_read_b128 v[40:43], v147 offset:32752
	ds_read_b64 v[66:67], v149 offset:34160
	v_mul_f32_e32 v120, v12, v32
	v_mul_f32_e32 v121, v16, v32
	v_mul_f32_e32 v122, v12, v36
	v_mul_f32_e32 v123, v16, v36
	v_fmac_f32_e32 v120, v13, v33
	v_fmac_f32_e32 v121, v17, v33
	v_fmac_f32_e32 v122, v13, v37
	v_fmac_f32_e32 v123, v17, v37
	v_fmac_f32_e32 v120, v14, v34
	v_fmac_f32_e32 v121, v18, v34
	v_fmac_f32_e32 v122, v14, v38
	v_fmac_f32_e32 v123, v18, v38
	v_fmac_f32_e32 v120, v15, v35
	v_fmac_f32_e32 v121, v19, v35
	v_fmac_f32_e32 v122, v15, v39
	v_fmac_f32_e32 v123, v19, v39
	v_cndmask_b32_e64 v124, v120, v121, s[42:43]
	v_cndmask_b32_e64 v126, v122, v123, s[42:43]
	v_cndmask_b32_e64 v125, v121, v120, s[42:43]
	v_cndmask_b32_e64 v127, v123, v122, s[42:43]
	v_add_f32_dpp v124, v124, v125 quad_perm:[1,0,3,2] row_mask:0xf bank_mask:0xf bound_ctrl:1
	v_add_f32_dpp v126, v126, v127 quad_perm:[1,0,3,2] row_mask:0xf bank_mask:0xf bound_ctrl:1
	v_cndmask_b32_e64 v128, v124, v126, s[44:45]
	v_cndmask_b32_e64 v129, v126, v124, s[44:45]
	v_pk_mul_f32 v[136:137], v[24:25], v[60:61] op_sel_hi:[1,0]
	v_add_f32_dpp v130, v128, v129 quad_perm:[2,3,0,1] row_mask:0xf bank_mask:0xf bound_ctrl:1
	v_pk_mul_f32 v[138:139], v[26:27], v[60:61] op_sel_hi:[1,0]
	v_pk_mul_f32 v[140:141], v[24:25], v[60:61] op_sel:[0,1]
	v_add_f32_dpp v130, v130, v130 row_ror:4 row_mask:0xf bank_mask:0xf bound_ctrl:1
	v_pk_mul_f32 v[142:143], v[26:27], v[60:61] op_sel:[0,1]
	v_cndmask_b32_e64 v145, v61, v60, s[42:43]
	v_add_f32_dpp v130, v130, v130 row_ror:8 row_mask:0xf bank_mask:0xf bound_ctrl:1
	v_cndmask_b32_e32 v5, v5, v150, vcc
	s_nop 0
	v_mov_b32_dpp v132, v130 quad_perm:[0,0,0,0] row_mask:0xf bank_mask:0xf bound_ctrl:1
	v_mov_b32_dpp v134, v130 quad_perm:[1,1,1,1] row_mask:0xf bank_mask:0xf bound_ctrl:1
	v_pk_fma_f32 v[136:137], v[28:29], v[132:133], v[136:137] op_sel_hi:[1,0,1]
	v_pk_fma_f32 v[138:139], v[30:31], v[132:133], v[138:139] op_sel_hi:[1,0,1]
	v_pk_fma_f32 v[140:141], v[28:29], v[134:135], v[140:141] op_sel_hi:[1,0,1]
	v_pk_fma_f32 v[142:143], v[30:31], v[134:135], v[142:143] op_sel_hi:[1,0,1]
	v_cndmask_b32_e64 v144, v134, v132, s[42:43]
	v_pk_fma_f32 v[12:13], v[12:13], v[20:21], v[136:137]
	v_pk_fma_f32 v[14:15], v[14:15], v[22:23], v[138:139]
	v_fma_f32 v146, v145, v65, v130
	v_pk_fma_f32 v[16:17], v[16:17], v[20:21], v[140:141]
	v_pk_fma_f32 v[18:19], v[18:19], v[22:23], v[142:143]
	v_fmac_f32_e32 v146, v144, v64
	s_waitcnt lgkmcnt(0)
	ds_read_b128 v[32:35], v147 offset:34944
	ds_read_b128 v[36:39], v147 offset:35200
	ds_read_b128 v[24:27], v147 offset:34432
	ds_read_b64 v[60:61], v148 offset:35456
	ds_read_b128 v[28:31], v147 offset:34688
	ds_read_b128 v[20:23], v147 offset:34176
	ds_read_b64 v[64:65], v149 offset:35584
	v_mul_f32_e32 v120, v12, v52
	v_mul_f32_e32 v121, v16, v52
	v_mul_f32_e32 v122, v12, v56
	v_mul_f32_e32 v123, v16, v56
	v_fmac_f32_e32 v120, v13, v53
	v_fmac_f32_e32 v121, v17, v53
	v_fmac_f32_e32 v122, v13, v57
	v_fmac_f32_e32 v123, v17, v57
	v_fmac_f32_e32 v120, v14, v54
	v_fmac_f32_e32 v121, v18, v54
	v_fmac_f32_e32 v122, v14, v58
	v_fmac_f32_e32 v123, v18, v58
	v_fmac_f32_e32 v120, v15, v55
	v_fmac_f32_e32 v121, v19, v55
	v_fmac_f32_e32 v122, v15, v59
	v_fmac_f32_e32 v123, v19, v59
	v_cndmask_b32_e64 v124, v120, v121, s[42:43]
	v_cndmask_b32_e64 v126, v122, v123, s[42:43]
	v_cndmask_b32_e64 v125, v121, v120, s[42:43]
	v_cndmask_b32_e64 v127, v123, v122, s[42:43]
	v_add_f32_dpp v124, v124, v125 quad_perm:[1,0,3,2] row_mask:0xf bank_mask:0xf bound_ctrl:1
	v_add_f32_dpp v126, v126, v127 quad_perm:[1,0,3,2] row_mask:0xf bank_mask:0xf bound_ctrl:1
	v_cndmask_b32_e64 v128, v124, v126, s[44:45]
	v_cndmask_b32_e64 v129, v126, v124, s[44:45]
	v_pk_mul_f32 v[136:137], v[44:45], v[62:63] op_sel_hi:[1,0]
	v_add_f32_dpp v130, v128, v129 quad_perm:[2,3,0,1] row_mask:0xf bank_mask:0xf bound_ctrl:1
	v_pk_mul_f32 v[138:139], v[46:47], v[62:63] op_sel_hi:[1,0]
	v_pk_mul_f32 v[140:141], v[44:45], v[62:63] op_sel:[0,1]
	v_add_f32_dpp v130, v130, v130 row_ror:4 row_mask:0xf bank_mask:0xf bound_ctrl:1
	v_pk_mul_f32 v[142:143], v[46:47], v[62:63] op_sel:[0,1]
	v_cndmask_b32_e64 v145, v63, v62, s[42:43]
	v_add_f32_dpp v130, v130, v130 row_ror:8 row_mask:0xf bank_mask:0xf bound_ctrl:1
	v_cndmask_b32_e32 v6, v6, v146, vcc
	s_nop 0
	v_mov_b32_dpp v132, v130 quad_perm:[0,0,0,0] row_mask:0xf bank_mask:0xf bound_ctrl:1
	v_mov_b32_dpp v134, v130 quad_perm:[1,1,1,1] row_mask:0xf bank_mask:0xf bound_ctrl:1
	v_pk_fma_f32 v[136:137], v[48:49], v[132:133], v[136:137] op_sel_hi:[1,0,1]
	v_pk_fma_f32 v[138:139], v[50:51], v[132:133], v[138:139] op_sel_hi:[1,0,1]
	v_pk_fma_f32 v[140:141], v[48:49], v[134:135], v[140:141] op_sel_hi:[1,0,1]
	v_pk_fma_f32 v[142:143], v[50:51], v[134:135], v[142:143] op_sel_hi:[1,0,1]
	v_cndmask_b32_e64 v144, v134, v132, s[42:43]
	v_pk_fma_f32 v[12:13], v[12:13], v[40:41], v[136:137]
	v_pk_fma_f32 v[14:15], v[14:15], v[42:43], v[138:139]
	v_fma_f32 v150, v145, v67, v130
	v_pk_fma_f32 v[16:17], v[16:17], v[40:41], v[140:141]
	v_pk_fma_f32 v[18:19], v[18:19], v[42:43], v[142:143]
	v_fmac_f32_e32 v150, v144, v66
	s_waitcnt lgkmcnt(0)
	ds_read_b128 v[52:55], v147 offset:36368
	ds_read_b128 v[56:59], v147 offset:36624
	ds_read_b128 v[44:47], v147 offset:35856
	ds_read_b64 v[62:63], v148 offset:36880
	ds_read_b128 v[48:51], v147 offset:36112
	ds_read_b128 v[40:43], v147 offset:35600
	ds_read_b64 v[66:67], v149 offset:37008
	v_mul_f32_e32 v120, v12, v32
	v_mul_f32_e32 v121, v16, v32
	v_mul_f32_e32 v122, v12, v36
	v_mul_f32_e32 v123, v16, v36
	v_fmac_f32_e32 v120, v13, v33
	v_fmac_f32_e32 v121, v17, v33
	v_fmac_f32_e32 v122, v13, v37
	v_fmac_f32_e32 v123, v17, v37
	v_fmac_f32_e32 v120, v14, v34
	v_fmac_f32_e32 v121, v18, v34
	v_fmac_f32_e32 v122, v14, v38
	v_fmac_f32_e32 v123, v18, v38
	v_fmac_f32_e32 v120, v15, v35
	v_fmac_f32_e32 v121, v19, v35
	v_fmac_f32_e32 v122, v15, v39
	v_fmac_f32_e32 v123, v19, v39
	v_cndmask_b32_e64 v124, v120, v121, s[42:43]
	v_cndmask_b32_e64 v126, v122, v123, s[42:43]
	v_cndmask_b32_e64 v125, v121, v120, s[42:43]
	v_cndmask_b32_e64 v127, v123, v122, s[42:43]
	v_add_f32_dpp v124, v124, v125 quad_perm:[1,0,3,2] row_mask:0xf bank_mask:0xf bound_ctrl:1
	v_add_f32_dpp v126, v126, v127 quad_perm:[1,0,3,2] row_mask:0xf bank_mask:0xf bound_ctrl:1
	v_cndmask_b32_e64 v128, v124, v126, s[44:45]
	v_cndmask_b32_e64 v129, v126, v124, s[44:45]
	v_pk_mul_f32 v[136:137], v[24:25], v[60:61] op_sel_hi:[1,0]
	v_add_f32_dpp v130, v128, v129 quad_perm:[2,3,0,1] row_mask:0xf bank_mask:0xf bound_ctrl:1
	v_pk_mul_f32 v[138:139], v[26:27], v[60:61] op_sel_hi:[1,0]
	v_pk_mul_f32 v[140:141], v[24:25], v[60:61] op_sel:[0,1]
	v_add_f32_dpp v130, v130, v130 row_ror:4 row_mask:0xf bank_mask:0xf bound_ctrl:1
	v_pk_mul_f32 v[142:143], v[26:27], v[60:61] op_sel:[0,1]
	v_cndmask_b32_e64 v145, v61, v60, s[42:43]
	v_add_f32_dpp v130, v130, v130 row_ror:8 row_mask:0xf bank_mask:0xf bound_ctrl:1
	v_cndmask_b32_e32 v7, v7, v150, vcc
	v_cmp_eq_u32_e32 vcc, 2, v119
	v_mov_b32_dpp v132, v130 quad_perm:[0,0,0,0] row_mask:0xf bank_mask:0xf bound_ctrl:1
	v_mov_b32_dpp v134, v130 quad_perm:[1,1,1,1] row_mask:0xf bank_mask:0xf bound_ctrl:1
	v_pk_fma_f32 v[136:137], v[28:29], v[132:133], v[136:137] op_sel_hi:[1,0,1]
	v_pk_fma_f32 v[138:139], v[30:31], v[132:133], v[138:139] op_sel_hi:[1,0,1]
	v_pk_fma_f32 v[140:141], v[28:29], v[134:135], v[140:141] op_sel_hi:[1,0,1]
	v_pk_fma_f32 v[142:143], v[30:31], v[134:135], v[142:143] op_sel_hi:[1,0,1]
	v_cndmask_b32_e64 v144, v134, v132, s[42:43]
	v_pk_fma_f32 v[12:13], v[12:13], v[20:21], v[136:137]
	v_pk_fma_f32 v[14:15], v[14:15], v[22:23], v[138:139]
	v_fma_f32 v146, v145, v65, v130
	v_pk_fma_f32 v[16:17], v[16:17], v[20:21], v[140:141]
	v_pk_fma_f32 v[18:19], v[18:19], v[22:23], v[142:143]
	v_fmac_f32_e32 v146, v144, v64
	s_waitcnt lgkmcnt(0)
	ds_read_b128 v[32:35], v147 offset:37792
	ds_read_b128 v[36:39], v147 offset:38048
	ds_read_b128 v[24:27], v147 offset:37280
	ds_read_b64 v[60:61], v148 offset:38304
	ds_read_b128 v[28:31], v147 offset:37536
	ds_read_b128 v[20:23], v147 offset:37024
	ds_read_b64 v[64:65], v149 offset:38432
	v_mul_f32_e32 v120, v12, v52
	v_mul_f32_e32 v121, v16, v52
	v_mul_f32_e32 v122, v12, v56
	v_mul_f32_e32 v123, v16, v56
	v_fmac_f32_e32 v120, v13, v53
	v_fmac_f32_e32 v121, v17, v53
	v_fmac_f32_e32 v122, v13, v57
	v_fmac_f32_e32 v123, v17, v57
	v_fmac_f32_e32 v120, v14, v54
	v_fmac_f32_e32 v121, v18, v54
	v_fmac_f32_e32 v122, v14, v58
	v_fmac_f32_e32 v123, v18, v58
	v_fmac_f32_e32 v120, v15, v55
	v_fmac_f32_e32 v121, v19, v55
	v_fmac_f32_e32 v122, v15, v59
	v_fmac_f32_e32 v123, v19, v59
	v_cndmask_b32_e64 v124, v120, v121, s[42:43]
	v_cndmask_b32_e64 v126, v122, v123, s[42:43]
	v_cndmask_b32_e64 v125, v121, v120, s[42:43]
	v_cndmask_b32_e64 v127, v123, v122, s[42:43]
	v_add_f32_dpp v124, v124, v125 quad_perm:[1,0,3,2] row_mask:0xf bank_mask:0xf bound_ctrl:1
	v_add_f32_dpp v126, v126, v127 quad_perm:[1,0,3,2] row_mask:0xf bank_mask:0xf bound_ctrl:1
	v_cndmask_b32_e64 v128, v124, v126, s[44:45]
	v_cndmask_b32_e64 v129, v126, v124, s[44:45]
	v_pk_mul_f32 v[136:137], v[44:45], v[62:63] op_sel_hi:[1,0]
	v_add_f32_dpp v130, v128, v129 quad_perm:[2,3,0,1] row_mask:0xf bank_mask:0xf bound_ctrl:1
	v_pk_mul_f32 v[138:139], v[46:47], v[62:63] op_sel_hi:[1,0]
	v_pk_mul_f32 v[140:141], v[44:45], v[62:63] op_sel:[0,1]
	v_add_f32_dpp v130, v130, v130 row_ror:4 row_mask:0xf bank_mask:0xf bound_ctrl:1
	v_pk_mul_f32 v[142:143], v[46:47], v[62:63] op_sel:[0,1]
	v_cndmask_b32_e64 v145, v63, v62, s[42:43]
	v_add_f32_dpp v130, v130, v130 row_ror:8 row_mask:0xf bank_mask:0xf bound_ctrl:1
	v_cndmask_b32_e32 v4, v4, v146, vcc
	s_nop 0
	v_mov_b32_dpp v132, v130 quad_perm:[0,0,0,0] row_mask:0xf bank_mask:0xf bound_ctrl:1
	v_mov_b32_dpp v134, v130 quad_perm:[1,1,1,1] row_mask:0xf bank_mask:0xf bound_ctrl:1
	v_pk_fma_f32 v[136:137], v[48:49], v[132:133], v[136:137] op_sel_hi:[1,0,1]
	v_pk_fma_f32 v[138:139], v[50:51], v[132:133], v[138:139] op_sel_hi:[1,0,1]
	v_pk_fma_f32 v[140:141], v[48:49], v[134:135], v[140:141] op_sel_hi:[1,0,1]
	v_pk_fma_f32 v[142:143], v[50:51], v[134:135], v[142:143] op_sel_hi:[1,0,1]
	v_cndmask_b32_e64 v144, v134, v132, s[42:43]
	v_pk_fma_f32 v[12:13], v[12:13], v[40:41], v[136:137]
	v_pk_fma_f32 v[14:15], v[14:15], v[42:43], v[138:139]
	v_fma_f32 v150, v145, v67, v130
	v_pk_fma_f32 v[16:17], v[16:17], v[40:41], v[140:141]
	v_pk_fma_f32 v[18:19], v[18:19], v[42:43], v[142:143]
	v_fmac_f32_e32 v150, v144, v66
	s_waitcnt lgkmcnt(0)
	ds_read_b128 v[52:55], v147 offset:39216
	ds_read_b128 v[56:59], v147 offset:39472
	ds_read_b128 v[44:47], v147 offset:38704
	ds_read_b64 v[62:63], v148 offset:39728
	ds_read_b128 v[48:51], v147 offset:38960
	ds_read_b128 v[40:43], v147 offset:38448
	ds_read_b64 v[66:67], v149 offset:39856
	v_mul_f32_e32 v120, v12, v32
	v_mul_f32_e32 v121, v16, v32
	v_mul_f32_e32 v122, v12, v36
	v_mul_f32_e32 v123, v16, v36
	v_fmac_f32_e32 v120, v13, v33
	v_fmac_f32_e32 v121, v17, v33
	v_fmac_f32_e32 v122, v13, v37
	v_fmac_f32_e32 v123, v17, v37
	v_fmac_f32_e32 v120, v14, v34
	v_fmac_f32_e32 v121, v18, v34
	v_fmac_f32_e32 v122, v14, v38
	v_fmac_f32_e32 v123, v18, v38
	v_fmac_f32_e32 v120, v15, v35
	v_fmac_f32_e32 v121, v19, v35
	v_fmac_f32_e32 v122, v15, v39
	v_fmac_f32_e32 v123, v19, v39
	v_cndmask_b32_e64 v124, v120, v121, s[42:43]
	v_cndmask_b32_e64 v126, v122, v123, s[42:43]
	v_cndmask_b32_e64 v125, v121, v120, s[42:43]
	v_cndmask_b32_e64 v127, v123, v122, s[42:43]
	v_add_f32_dpp v124, v124, v125 quad_perm:[1,0,3,2] row_mask:0xf bank_mask:0xf bound_ctrl:1
	v_add_f32_dpp v126, v126, v127 quad_perm:[1,0,3,2] row_mask:0xf bank_mask:0xf bound_ctrl:1
	v_cndmask_b32_e64 v128, v124, v126, s[44:45]
	v_cndmask_b32_e64 v129, v126, v124, s[44:45]
	v_pk_mul_f32 v[136:137], v[24:25], v[60:61] op_sel_hi:[1,0]
	v_add_f32_dpp v130, v128, v129 quad_perm:[2,3,0,1] row_mask:0xf bank_mask:0xf bound_ctrl:1
	v_pk_mul_f32 v[138:139], v[26:27], v[60:61] op_sel_hi:[1,0]
	v_pk_mul_f32 v[140:141], v[24:25], v[60:61] op_sel:[0,1]
	v_add_f32_dpp v130, v130, v130 row_ror:4 row_mask:0xf bank_mask:0xf bound_ctrl:1
	v_pk_mul_f32 v[142:143], v[26:27], v[60:61] op_sel:[0,1]
	v_cndmask_b32_e64 v145, v61, v60, s[42:43]
	v_add_f32_dpp v130, v130, v130 row_ror:8 row_mask:0xf bank_mask:0xf bound_ctrl:1
	v_cndmask_b32_e32 v5, v5, v150, vcc
	s_nop 0
	v_mov_b32_dpp v132, v130 quad_perm:[0,0,0,0] row_mask:0xf bank_mask:0xf bound_ctrl:1
	v_mov_b32_dpp v134, v130 quad_perm:[1,1,1,1] row_mask:0xf bank_mask:0xf bound_ctrl:1
	v_pk_fma_f32 v[136:137], v[28:29], v[132:133], v[136:137] op_sel_hi:[1,0,1]
	v_pk_fma_f32 v[138:139], v[30:31], v[132:133], v[138:139] op_sel_hi:[1,0,1]
	v_pk_fma_f32 v[140:141], v[28:29], v[134:135], v[140:141] op_sel_hi:[1,0,1]
	v_pk_fma_f32 v[142:143], v[30:31], v[134:135], v[142:143] op_sel_hi:[1,0,1]
	v_cndmask_b32_e64 v144, v134, v132, s[42:43]
	v_pk_fma_f32 v[12:13], v[12:13], v[20:21], v[136:137]
	v_pk_fma_f32 v[14:15], v[14:15], v[22:23], v[138:139]
	v_fma_f32 v146, v145, v65, v130
	v_pk_fma_f32 v[16:17], v[16:17], v[20:21], v[140:141]
	v_pk_fma_f32 v[18:19], v[18:19], v[22:23], v[142:143]
	v_fmac_f32_e32 v146, v144, v64
	s_waitcnt lgkmcnt(0)
	ds_read_b128 v[32:35], v147 offset:40640
	ds_read_b128 v[36:39], v147 offset:40896
	ds_read_b128 v[24:27], v147 offset:40128
	ds_read_b64 v[60:61], v148 offset:41152
	ds_read_b128 v[28:31], v147 offset:40384
	ds_read_b128 v[20:23], v147 offset:39872
	ds_read_b64 v[64:65], v149 offset:41280
	v_mul_f32_e32 v120, v12, v52
	v_mul_f32_e32 v121, v16, v52
	v_mul_f32_e32 v122, v12, v56
	v_mul_f32_e32 v123, v16, v56
	v_fmac_f32_e32 v120, v13, v53
	v_fmac_f32_e32 v121, v17, v53
	v_fmac_f32_e32 v122, v13, v57
	v_fmac_f32_e32 v123, v17, v57
	v_fmac_f32_e32 v120, v14, v54
	v_fmac_f32_e32 v121, v18, v54
	v_fmac_f32_e32 v122, v14, v58
	v_fmac_f32_e32 v123, v18, v58
	v_fmac_f32_e32 v120, v15, v55
	v_fmac_f32_e32 v121, v19, v55
	v_fmac_f32_e32 v122, v15, v59
	v_fmac_f32_e32 v123, v19, v59
	v_cndmask_b32_e64 v124, v120, v121, s[42:43]
	v_cndmask_b32_e64 v126, v122, v123, s[42:43]
	v_cndmask_b32_e64 v125, v121, v120, s[42:43]
	v_cndmask_b32_e64 v127, v123, v122, s[42:43]
	v_add_f32_dpp v124, v124, v125 quad_perm:[1,0,3,2] row_mask:0xf bank_mask:0xf bound_ctrl:1
	v_add_f32_dpp v126, v126, v127 quad_perm:[1,0,3,2] row_mask:0xf bank_mask:0xf bound_ctrl:1
	v_cndmask_b32_e64 v128, v124, v126, s[44:45]
	v_cndmask_b32_e64 v129, v126, v124, s[44:45]
	v_pk_mul_f32 v[136:137], v[44:45], v[62:63] op_sel_hi:[1,0]
	v_add_f32_dpp v130, v128, v129 quad_perm:[2,3,0,1] row_mask:0xf bank_mask:0xf bound_ctrl:1
	v_pk_mul_f32 v[138:139], v[46:47], v[62:63] op_sel_hi:[1,0]
	v_pk_mul_f32 v[140:141], v[44:45], v[62:63] op_sel:[0,1]
	v_add_f32_dpp v130, v130, v130 row_ror:4 row_mask:0xf bank_mask:0xf bound_ctrl:1
	v_pk_mul_f32 v[142:143], v[46:47], v[62:63] op_sel:[0,1]
	v_cndmask_b32_e64 v145, v63, v62, s[42:43]
	v_add_f32_dpp v130, v130, v130 row_ror:8 row_mask:0xf bank_mask:0xf bound_ctrl:1
	v_cndmask_b32_e32 v6, v6, v146, vcc
	s_nop 0
	v_mov_b32_dpp v132, v130 quad_perm:[0,0,0,0] row_mask:0xf bank_mask:0xf bound_ctrl:1
	v_mov_b32_dpp v134, v130 quad_perm:[1,1,1,1] row_mask:0xf bank_mask:0xf bound_ctrl:1
	v_pk_fma_f32 v[136:137], v[48:49], v[132:133], v[136:137] op_sel_hi:[1,0,1]
	v_pk_fma_f32 v[138:139], v[50:51], v[132:133], v[138:139] op_sel_hi:[1,0,1]
	v_pk_fma_f32 v[140:141], v[48:49], v[134:135], v[140:141] op_sel_hi:[1,0,1]
	v_pk_fma_f32 v[142:143], v[50:51], v[134:135], v[142:143] op_sel_hi:[1,0,1]
	v_cndmask_b32_e64 v144, v134, v132, s[42:43]
	v_pk_fma_f32 v[12:13], v[12:13], v[40:41], v[136:137]
	v_pk_fma_f32 v[14:15], v[14:15], v[42:43], v[138:139]
	v_fma_f32 v150, v145, v67, v130
	v_pk_fma_f32 v[16:17], v[16:17], v[40:41], v[140:141]
	v_pk_fma_f32 v[18:19], v[18:19], v[42:43], v[142:143]
	v_fmac_f32_e32 v150, v144, v66
	s_waitcnt lgkmcnt(0)
	ds_read_b128 v[52:55], v147 offset:42064
	ds_read_b128 v[56:59], v147 offset:42320
	ds_read_b128 v[44:47], v147 offset:41552
	ds_read_b64 v[62:63], v148 offset:42576
	ds_read_b128 v[48:51], v147 offset:41808
	ds_read_b128 v[40:43], v147 offset:41296
	ds_read_b64 v[66:67], v149 offset:42704
	v_mul_f32_e32 v120, v12, v32
	v_mul_f32_e32 v121, v16, v32
	v_mul_f32_e32 v122, v12, v36
	v_mul_f32_e32 v123, v16, v36
	v_fmac_f32_e32 v120, v13, v33
	v_fmac_f32_e32 v121, v17, v33
	v_fmac_f32_e32 v122, v13, v37
	v_fmac_f32_e32 v123, v17, v37
	v_fmac_f32_e32 v120, v14, v34
	v_fmac_f32_e32 v121, v18, v34
	v_fmac_f32_e32 v122, v14, v38
	v_fmac_f32_e32 v123, v18, v38
	v_fmac_f32_e32 v120, v15, v35
	v_fmac_f32_e32 v121, v19, v35
	v_fmac_f32_e32 v122, v15, v39
	v_fmac_f32_e32 v123, v19, v39
	v_cndmask_b32_e64 v124, v120, v121, s[42:43]
	v_cndmask_b32_e64 v126, v122, v123, s[42:43]
	v_cndmask_b32_e64 v125, v121, v120, s[42:43]
	v_cndmask_b32_e64 v127, v123, v122, s[42:43]
	v_add_f32_dpp v124, v124, v125 quad_perm:[1,0,3,2] row_mask:0xf bank_mask:0xf bound_ctrl:1
	v_add_f32_dpp v126, v126, v127 quad_perm:[1,0,3,2] row_mask:0xf bank_mask:0xf bound_ctrl:1
	v_cndmask_b32_e64 v128, v124, v126, s[44:45]
	v_cndmask_b32_e64 v129, v126, v124, s[44:45]
	v_pk_mul_f32 v[136:137], v[24:25], v[60:61] op_sel_hi:[1,0]
	v_add_f32_dpp v130, v128, v129 quad_perm:[2,3,0,1] row_mask:0xf bank_mask:0xf bound_ctrl:1
	v_pk_mul_f32 v[138:139], v[26:27], v[60:61] op_sel_hi:[1,0]
	v_pk_mul_f32 v[140:141], v[24:25], v[60:61] op_sel:[0,1]
	v_add_f32_dpp v130, v130, v130 row_ror:4 row_mask:0xf bank_mask:0xf bound_ctrl:1
	v_pk_mul_f32 v[142:143], v[26:27], v[60:61] op_sel:[0,1]
	v_cndmask_b32_e64 v145, v61, v60, s[42:43]
	v_add_f32_dpp v130, v130, v130 row_ror:8 row_mask:0xf bank_mask:0xf bound_ctrl:1
	v_cndmask_b32_e32 v7, v7, v150, vcc
	v_cmp_eq_u32_e32 vcc, 3, v119
	v_mov_b32_dpp v132, v130 quad_perm:[0,0,0,0] row_mask:0xf bank_mask:0xf bound_ctrl:1
	v_mov_b32_dpp v134, v130 quad_perm:[1,1,1,1] row_mask:0xf bank_mask:0xf bound_ctrl:1
	v_pk_fma_f32 v[136:137], v[28:29], v[132:133], v[136:137] op_sel_hi:[1,0,1]
	v_pk_fma_f32 v[138:139], v[30:31], v[132:133], v[138:139] op_sel_hi:[1,0,1]
	v_pk_fma_f32 v[140:141], v[28:29], v[134:135], v[140:141] op_sel_hi:[1,0,1]
	v_pk_fma_f32 v[142:143], v[30:31], v[134:135], v[142:143] op_sel_hi:[1,0,1]
	v_cndmask_b32_e64 v144, v134, v132, s[42:43]
	v_pk_fma_f32 v[12:13], v[12:13], v[20:21], v[136:137]
	v_pk_fma_f32 v[14:15], v[14:15], v[22:23], v[138:139]
	v_fma_f32 v146, v145, v65, v130
	v_pk_fma_f32 v[16:17], v[16:17], v[20:21], v[140:141]
	v_pk_fma_f32 v[18:19], v[18:19], v[22:23], v[142:143]
	v_fmac_f32_e32 v146, v144, v64
	s_waitcnt lgkmcnt(0)
	ds_read_b128 v[32:35], v147 offset:43488
	ds_read_b128 v[36:39], v147 offset:43744
	ds_read_b128 v[24:27], v147 offset:42976
	ds_read_b64 v[60:61], v148 offset:44000
	ds_read_b128 v[28:31], v147 offset:43232
	ds_read_b128 v[20:23], v147 offset:42720
	ds_read_b64 v[64:65], v149 offset:44128
	v_mul_f32_e32 v120, v12, v52
	v_mul_f32_e32 v121, v16, v52
	v_mul_f32_e32 v122, v12, v56
	v_mul_f32_e32 v123, v16, v56
	v_fmac_f32_e32 v120, v13, v53
	v_fmac_f32_e32 v121, v17, v53
	v_fmac_f32_e32 v122, v13, v57
	v_fmac_f32_e32 v123, v17, v57
	v_fmac_f32_e32 v120, v14, v54
	v_fmac_f32_e32 v121, v18, v54
	v_fmac_f32_e32 v122, v14, v58
	v_fmac_f32_e32 v123, v18, v58
	v_fmac_f32_e32 v120, v15, v55
	v_fmac_f32_e32 v121, v19, v55
	v_fmac_f32_e32 v122, v15, v59
	v_fmac_f32_e32 v123, v19, v59
	v_cndmask_b32_e64 v124, v120, v121, s[42:43]
	v_cndmask_b32_e64 v126, v122, v123, s[42:43]
	v_cndmask_b32_e64 v125, v121, v120, s[42:43]
	v_cndmask_b32_e64 v127, v123, v122, s[42:43]
	v_add_f32_dpp v124, v124, v125 quad_perm:[1,0,3,2] row_mask:0xf bank_mask:0xf bound_ctrl:1
	v_add_f32_dpp v126, v126, v127 quad_perm:[1,0,3,2] row_mask:0xf bank_mask:0xf bound_ctrl:1
	v_cndmask_b32_e64 v128, v124, v126, s[44:45]
	v_cndmask_b32_e64 v129, v126, v124, s[44:45]
	v_pk_mul_f32 v[136:137], v[44:45], v[62:63] op_sel_hi:[1,0]
	v_add_f32_dpp v130, v128, v129 quad_perm:[2,3,0,1] row_mask:0xf bank_mask:0xf bound_ctrl:1
	v_pk_mul_f32 v[138:139], v[46:47], v[62:63] op_sel_hi:[1,0]
	v_pk_mul_f32 v[140:141], v[44:45], v[62:63] op_sel:[0,1]
	v_add_f32_dpp v130, v130, v130 row_ror:4 row_mask:0xf bank_mask:0xf bound_ctrl:1
	v_pk_mul_f32 v[142:143], v[46:47], v[62:63] op_sel:[0,1]
	v_cndmask_b32_e64 v145, v63, v62, s[42:43]
	v_add_f32_dpp v130, v130, v130 row_ror:8 row_mask:0xf bank_mask:0xf bound_ctrl:1
	v_cndmask_b32_e32 v4, v4, v146, vcc
	s_nop 0
	v_mov_b32_dpp v132, v130 quad_perm:[0,0,0,0] row_mask:0xf bank_mask:0xf bound_ctrl:1
	v_mov_b32_dpp v134, v130 quad_perm:[1,1,1,1] row_mask:0xf bank_mask:0xf bound_ctrl:1
	v_pk_fma_f32 v[136:137], v[48:49], v[132:133], v[136:137] op_sel_hi:[1,0,1]
	v_pk_fma_f32 v[138:139], v[50:51], v[132:133], v[138:139] op_sel_hi:[1,0,1]
	v_pk_fma_f32 v[140:141], v[48:49], v[134:135], v[140:141] op_sel_hi:[1,0,1]
	v_pk_fma_f32 v[142:143], v[50:51], v[134:135], v[142:143] op_sel_hi:[1,0,1]
	v_cndmask_b32_e64 v144, v134, v132, s[42:43]
	v_pk_fma_f32 v[12:13], v[12:13], v[40:41], v[136:137]
	v_pk_fma_f32 v[14:15], v[14:15], v[42:43], v[138:139]
	v_fma_f32 v150, v145, v67, v130
	v_pk_fma_f32 v[16:17], v[16:17], v[40:41], v[140:141]
	v_pk_fma_f32 v[18:19], v[18:19], v[42:43], v[142:143]
	v_fmac_f32_e32 v150, v144, v66
	s_waitcnt lgkmcnt(0)
	ds_read_b128 v[52:55], v147 offset:44912
	ds_read_b128 v[56:59], v147 offset:45168
	ds_read_b128 v[44:47], v147 offset:44400
	ds_read_b64 v[62:63], v148 offset:45424
	ds_read_b128 v[48:51], v147 offset:44656
	ds_read_b128 v[40:43], v147 offset:44144
	ds_read_b64 v[66:67], v149 offset:45552
	v_mul_f32_e32 v120, v12, v32
	v_mul_f32_e32 v121, v16, v32
	v_mul_f32_e32 v122, v12, v36
	v_mul_f32_e32 v123, v16, v36
	v_fmac_f32_e32 v120, v13, v33
	v_fmac_f32_e32 v121, v17, v33
	v_fmac_f32_e32 v122, v13, v37
	v_fmac_f32_e32 v123, v17, v37
	v_fmac_f32_e32 v120, v14, v34
	v_fmac_f32_e32 v121, v18, v34
	v_fmac_f32_e32 v122, v14, v38
	v_fmac_f32_e32 v123, v18, v38
	v_fmac_f32_e32 v120, v15, v35
	v_fmac_f32_e32 v121, v19, v35
	v_fmac_f32_e32 v122, v15, v39
	v_fmac_f32_e32 v123, v19, v39
	v_cndmask_b32_e64 v124, v120, v121, s[42:43]
	v_cndmask_b32_e64 v126, v122, v123, s[42:43]
	v_cndmask_b32_e64 v125, v121, v120, s[42:43]
	v_cndmask_b32_e64 v127, v123, v122, s[42:43]
	v_add_f32_dpp v124, v124, v125 quad_perm:[1,0,3,2] row_mask:0xf bank_mask:0xf bound_ctrl:1
	v_add_f32_dpp v126, v126, v127 quad_perm:[1,0,3,2] row_mask:0xf bank_mask:0xf bound_ctrl:1
	v_cndmask_b32_e64 v128, v124, v126, s[44:45]
	v_cndmask_b32_e64 v129, v126, v124, s[44:45]
	v_pk_mul_f32 v[136:137], v[24:25], v[60:61] op_sel_hi:[1,0]
	v_add_f32_dpp v130, v128, v129 quad_perm:[2,3,0,1] row_mask:0xf bank_mask:0xf bound_ctrl:1
	v_pk_mul_f32 v[138:139], v[26:27], v[60:61] op_sel_hi:[1,0]
	v_pk_mul_f32 v[140:141], v[24:25], v[60:61] op_sel:[0,1]
	v_add_f32_dpp v130, v130, v130 row_ror:4 row_mask:0xf bank_mask:0xf bound_ctrl:1
	v_pk_mul_f32 v[142:143], v[26:27], v[60:61] op_sel:[0,1]
	v_cndmask_b32_e64 v145, v61, v60, s[42:43]
	v_add_f32_dpp v130, v130, v130 row_ror:8 row_mask:0xf bank_mask:0xf bound_ctrl:1
	v_cndmask_b32_e32 v5, v5, v150, vcc
	s_nop 0
	v_mov_b32_dpp v132, v130 quad_perm:[0,0,0,0] row_mask:0xf bank_mask:0xf bound_ctrl:1
	v_mov_b32_dpp v134, v130 quad_perm:[1,1,1,1] row_mask:0xf bank_mask:0xf bound_ctrl:1
	v_pk_fma_f32 v[136:137], v[28:29], v[132:133], v[136:137] op_sel_hi:[1,0,1]
	v_pk_fma_f32 v[138:139], v[30:31], v[132:133], v[138:139] op_sel_hi:[1,0,1]
	v_pk_fma_f32 v[140:141], v[28:29], v[134:135], v[140:141] op_sel_hi:[1,0,1]
	v_pk_fma_f32 v[142:143], v[30:31], v[134:135], v[142:143] op_sel_hi:[1,0,1]
	v_cndmask_b32_e64 v144, v134, v132, s[42:43]
	v_pk_fma_f32 v[12:13], v[12:13], v[20:21], v[136:137]
	v_pk_fma_f32 v[14:15], v[14:15], v[22:23], v[138:139]
	v_fma_f32 v146, v145, v65, v130
	v_pk_fma_f32 v[16:17], v[16:17], v[20:21], v[140:141]
	v_pk_fma_f32 v[18:19], v[18:19], v[22:23], v[142:143]
	v_fmac_f32_e32 v146, v144, v64
	s_waitcnt lgkmcnt(0)
	v_mul_f32_e32 v120, v12, v52
	v_mul_f32_e32 v121, v16, v52
	v_mul_f32_e32 v122, v12, v56
	v_mul_f32_e32 v123, v16, v56
	v_fmac_f32_e32 v120, v13, v53
	v_fmac_f32_e32 v121, v17, v53
	v_fmac_f32_e32 v122, v13, v57
	v_fmac_f32_e32 v123, v17, v57
	v_fmac_f32_e32 v120, v14, v54
	v_fmac_f32_e32 v121, v18, v54
	v_fmac_f32_e32 v122, v14, v58
	v_fmac_f32_e32 v123, v18, v58
	v_fmac_f32_e32 v120, v15, v55
	v_fmac_f32_e32 v121, v19, v55
	v_fmac_f32_e32 v122, v15, v59
	v_fmac_f32_e32 v123, v19, v59
	v_cndmask_b32_e64 v124, v120, v121, s[42:43]
	v_cndmask_b32_e64 v126, v122, v123, s[42:43]
	v_cndmask_b32_e64 v125, v121, v120, s[42:43]
	v_cndmask_b32_e64 v127, v123, v122, s[42:43]
	v_add_f32_dpp v124, v124, v125 quad_perm:[1,0,3,2] row_mask:0xf bank_mask:0xf bound_ctrl:1
	v_add_f32_dpp v126, v126, v127 quad_perm:[1,0,3,2] row_mask:0xf bank_mask:0xf bound_ctrl:1
	v_cndmask_b32_e64 v128, v124, v126, s[44:45]
	v_cndmask_b32_e64 v129, v126, v124, s[44:45]
	v_pk_mul_f32 v[136:137], v[44:45], v[62:63] op_sel_hi:[1,0]
	v_add_f32_dpp v130, v128, v129 quad_perm:[2,3,0,1] row_mask:0xf bank_mask:0xf bound_ctrl:1
	v_pk_mul_f32 v[138:139], v[46:47], v[62:63] op_sel_hi:[1,0]
	v_pk_mul_f32 v[140:141], v[44:45], v[62:63] op_sel:[0,1]
	v_add_f32_dpp v130, v130, v130 row_ror:4 row_mask:0xf bank_mask:0xf bound_ctrl:1
	v_pk_mul_f32 v[142:143], v[46:47], v[62:63] op_sel:[0,1]
	v_cndmask_b32_e64 v145, v63, v62, s[42:43]
	v_add_f32_dpp v130, v130, v130 row_ror:8 row_mask:0xf bank_mask:0xf bound_ctrl:1
	v_cndmask_b32_e32 v6, v6, v146, vcc
	s_nop 0
	v_mov_b32_dpp v132, v130 quad_perm:[0,0,0,0] row_mask:0xf bank_mask:0xf bound_ctrl:1
	v_mov_b32_dpp v134, v130 quad_perm:[1,1,1,1] row_mask:0xf bank_mask:0xf bound_ctrl:1
	v_pk_fma_f32 v[136:137], v[48:49], v[132:133], v[136:137] op_sel_hi:[1,0,1]
	v_pk_fma_f32 v[138:139], v[50:51], v[132:133], v[138:139] op_sel_hi:[1,0,1]
	v_pk_fma_f32 v[140:141], v[48:49], v[134:135], v[140:141] op_sel_hi:[1,0,1]
	v_pk_fma_f32 v[142:143], v[50:51], v[134:135], v[142:143] op_sel_hi:[1,0,1]
	v_cndmask_b32_e64 v144, v134, v132, s[42:43]
	v_pk_fma_f32 v[12:13], v[12:13], v[40:41], v[136:137]
	v_pk_fma_f32 v[14:15], v[14:15], v[42:43], v[138:139]
	v_fma_f32 v150, v145, v67, v130
	v_pk_fma_f32 v[16:17], v[16:17], v[40:41], v[140:141]
	v_pk_fma_f32 v[18:19], v[18:19], v[42:43], v[142:143]
	v_fmac_f32_e32 v150, v144, v66
	s_nop 0
	v_cndmask_b32_e32 v7, v7, v150, vcc
	s_setprio 0
	s_and_saveexec_b64 s[78:79], s[46:47]
	s_cbranch_execz .LBB0_458
	s_waitcnt lgkmcnt(8)
	v_lshl_add_u32 v20, s22, 12, v115
	ds_write2_b32 v20, v0, v1 offset1:32
	ds_write2_b32 v20, v2, v3 offset0:64 offset1:96
	v_add_u32_e32 v0, 0x800, v20
	ds_write2_b32 v0, v4, v5 offset1:32
	ds_write2_b32 v0, v6, v7 offset0:64 offset1:96
